# K-loops: load-segment end = s_setprio 1; one merged s_waitcnt vmcnt(8) lgkmcnt(0); s_barrier (on top of prio-before-barrier + P0 item pipeline)
# speedup vs baseline: 1.1082x; 1.1082x over previous
.LBB0_446:
	ds_read_b128 v[148:151], v165
	ds_read_b128 v[174:177], v165 offset:1024
	ds_read_b128 v[180:183], v165 offset:2048
	ds_read_b128 v[184:187], v165 offset:3072
	ds_read_b128 v[188:191], v169
	ds_read_b128 v[192:195], v169 offset:1024
	ds_read_b128 v[196:199], v169 offset:2048
	ds_read_b128 v[200:203], v169 offset:3072
	s_add_u32 s50, s4, 0xfff00080
	s_addc_u32 s51, s5, -1
	s_cmp_eq_u32 s68, 60
	s_cselect_b32 s53, s3, s51
	s_cselect_b32 s52, s8, s50
	s_cselect_b32 s51, s39, s65
	s_cselect_b32 s50, s45, s63
	v_lshl_add_u64 v[154:155], s[4:5], 0, v[140:141]
	s_add_i32 m0, s7, 0xc000
	ds_read_b128 v[204:207], v173
	ds_read_b128 v[208:211], v173 offset:1024
	ds_read_b128 v[212:215], v173 offset:2048
	ds_read_b128 v[216:219], v173 offset:3072
	ds_read_b128 v[220:223], v173 offset:4096
	ds_read_b128 v[224:227], v173 offset:5120
	ds_read_b128 v[228:231], v173 offset:6144
	ds_read_b128 v[236:239], v173 offset:7168
	global_load_lds_dwordx4 v[154:155], off
	v_lshl_add_u64 v[154:155], s[4:5], 0, v[142:143]
	s_add_i32 m0, s7, 0xe000
	s_nop 0
	global_load_lds_dwordx4 v[154:155], off
	s_setprio 1
	s_waitcnt vmcnt(8) lgkmcnt(0)
	s_barrier
	v_mfma_f32_16x16x32_bf16 v[126:129], v[148:151], v[204:207], v[126:129]
	v_mfma_f32_16x16x32_bf16 v[122:125], v[180:183], v[204:207], v[122:125]
	v_mfma_f32_16x16x32_bf16 v[110:113], v[148:151], v[212:215], v[110:113]
	v_mfma_f32_16x16x32_bf16 v[106:109], v[180:183], v[212:215], v[106:109]
	v_mfma_f32_16x16x32_bf16 v[94:97], v[148:151], v[220:223], v[94:97]
	v_mfma_f32_16x16x32_bf16 v[90:93], v[180:183], v[220:223], v[90:93]
	v_mfma_f32_16x16x32_bf16 v[78:81], v[148:151], v[228:231], v[78:81]
	v_mfma_f32_16x16x32_bf16 v[74:77], v[180:183], v[228:231], v[74:77]
	v_mfma_f32_16x16x32_bf16 v[126:129], v[174:177], v[208:211], v[126:129]
	v_mfma_f32_16x16x32_bf16 v[122:125], v[184:187], v[208:211], v[122:125]
	v_mfma_f32_16x16x32_bf16 v[110:113], v[174:177], v[216:219], v[110:113]
	v_mfma_f32_16x16x32_bf16 v[106:109], v[184:187], v[216:219], v[106:109]
	v_mfma_f32_16x16x32_bf16 v[94:97], v[174:177], v[224:227], v[94:97]
	v_mfma_f32_16x16x32_bf16 v[90:93], v[184:187], v[224:227], v[90:93]
	v_mfma_f32_16x16x32_bf16 v[78:81], v[174:177], v[236:239], v[78:81]
	v_mfma_f32_16x16x32_bf16 v[74:77], v[184:187], v[236:239], v[74:77]
	v_mfma_f32_16x16x32_bf16 v[118:121], v[188:191], v[204:207], v[118:121]
	v_mfma_f32_16x16x32_bf16 v[114:117], v[196:199], v[204:207], v[114:117]
	v_mfma_f32_16x16x32_bf16 v[102:105], v[188:191], v[212:215], v[102:105]
	v_mfma_f32_16x16x32_bf16 v[98:101], v[196:199], v[212:215], v[98:101]
	v_mfma_f32_16x16x32_bf16 v[86:89], v[188:191], v[220:223], v[86:89]
	v_mfma_f32_16x16x32_bf16 v[82:85], v[196:199], v[220:223], v[82:85]
	v_mfma_f32_16x16x32_bf16 v[70:73], v[188:191], v[228:231], v[70:73]
	v_mfma_f32_16x16x32_bf16 v[66:69], v[196:199], v[228:231], v[66:69]
	v_mfma_f32_16x16x32_bf16 v[118:121], v[192:195], v[208:211], v[118:121]
	v_mfma_f32_16x16x32_bf16 v[114:117], v[200:203], v[208:211], v[114:117]
	v_mfma_f32_16x16x32_bf16 v[102:105], v[192:195], v[216:219], v[102:105]
	v_mfma_f32_16x16x32_bf16 v[98:101], v[200:203], v[216:219], v[98:101]
	v_mfma_f32_16x16x32_bf16 v[86:89], v[192:195], v[224:227], v[86:89]
	v_mfma_f32_16x16x32_bf16 v[82:85], v[200:203], v[224:227], v[82:85]
	v_mfma_f32_16x16x32_bf16 v[70:73], v[192:195], v[236:239], v[70:73]
	v_mfma_f32_16x16x32_bf16 v[66:69], v[200:203], v[236:239], v[66:69]
	s_barrier
	s_setprio 0
	s_add_i32 s69, s59, s35
	v_lshl_add_u64 v[154:155], s[50:51], 0, v[132:133]
	s_mov_b32 m0, s69
	ds_read_b128 v[204:207], v173 offset:16384
	ds_read_b128 v[208:211], v173 offset:17408
	ds_read_b128 v[212:215], v173 offset:18432
	ds_read_b128 v[216:219], v173 offset:19456
	ds_read_b128 v[220:223], v173 offset:20480
	ds_read_b128 v[224:227], v173 offset:21504
	ds_read_b128 v[228:231], v173 offset:22528
	ds_read_b128 v[236:239], v173 offset:23552
	global_load_lds_dwordx4 v[154:155], off
	s_add_i32 m0, s69, 0x2000
	s_add_u32 s70, s50, 0x100000
	v_lshl_add_u64 v[158:159], s[50:51], 0, v[136:137]
	s_addc_u32 s71, s51, 0
	s_add_i32 s69, s60, s35
	global_load_lds_dwordx4 v[158:159], off
	v_lshl_add_u64 v[162:163], s[70:71], 0, v[132:133]
	s_mov_b32 m0, s69
	v_lshl_add_u64 v[166:167], s[52:53], 0, v[134:135]
	global_load_lds_dwordx4 v[162:163], off
	v_lshl_add_u64 v[162:163], s[70:71], 0, v[136:137]
	s_add_i32 m0, s69, 0x2000
	s_nop 0
	global_load_lds_dwordx4 v[162:163], off
	v_lshl_add_u64 v[162:163], s[52:53], 0, v[130:131]
	s_mov_b32 m0, s7
	s_nop 0
	global_load_lds_dwordx4 v[162:163], off
	s_mov_b32 m0, s37
	s_nop 0
	global_load_lds_dwordx4 v[166:167], off
	s_setprio 1
	s_waitcnt vmcnt(8) lgkmcnt(0)
	s_barrier
	v_mfma_f32_16x16x32_bf16 v[62:65], v[148:151], v[204:207], v[62:65]
	v_mfma_f32_16x16x32_bf16 v[58:61], v[180:183], v[204:207], v[58:61]
	v_mfma_f32_16x16x32_bf16 v[46:49], v[148:151], v[212:215], v[46:49]
	v_mfma_f32_16x16x32_bf16 v[42:45], v[180:183], v[212:215], v[42:45]
	v_mfma_f32_16x16x32_bf16 v[30:33], v[148:151], v[220:223], v[30:33]
	v_mfma_f32_16x16x32_bf16 v[26:29], v[180:183], v[220:223], v[26:29]
	v_mfma_f32_16x16x32_bf16 v[14:17], v[148:151], v[228:231], v[14:17]
	v_mfma_f32_16x16x32_bf16 v[10:13], v[180:183], v[228:231], v[10:13]
	v_mfma_f32_16x16x32_bf16 v[62:65], v[174:177], v[208:211], v[62:65]
	v_mfma_f32_16x16x32_bf16 v[58:61], v[184:187], v[208:211], v[58:61]
	v_mfma_f32_16x16x32_bf16 v[46:49], v[174:177], v[216:219], v[46:49]
	v_mfma_f32_16x16x32_bf16 v[42:45], v[184:187], v[216:219], v[42:45]
	v_mfma_f32_16x16x32_bf16 v[30:33], v[174:177], v[224:227], v[30:33]
	v_mfma_f32_16x16x32_bf16 v[26:29], v[184:187], v[224:227], v[26:29]
	v_mfma_f32_16x16x32_bf16 v[14:17], v[174:177], v[236:239], v[14:17]
	v_mfma_f32_16x16x32_bf16 v[10:13], v[184:187], v[236:239], v[10:13]
	v_mfma_f32_16x16x32_bf16 v[54:57], v[188:191], v[204:207], v[54:57]
	v_mfma_f32_16x16x32_bf16 v[50:53], v[196:199], v[204:207], v[50:53]
	v_mfma_f32_16x16x32_bf16 v[38:41], v[188:191], v[212:215], v[38:41]
	v_mfma_f32_16x16x32_bf16 v[34:37], v[196:199], v[212:215], v[34:37]
	v_mfma_f32_16x16x32_bf16 v[22:25], v[188:191], v[220:223], v[22:25]
	v_mfma_f32_16x16x32_bf16 v[18:21], v[196:199], v[220:223], v[18:21]
	v_mfma_f32_16x16x32_bf16 v[6:9], v[188:191], v[228:231], v[6:9]
	v_mfma_f32_16x16x32_bf16 v[2:5], v[196:199], v[228:231], v[2:5]
	v_mfma_f32_16x16x32_bf16 v[54:57], v[192:195], v[208:211], v[54:57]
	v_mfma_f32_16x16x32_bf16 v[50:53], v[200:203], v[208:211], v[50:53]
	v_mfma_f32_16x16x32_bf16 v[38:41], v[192:195], v[216:219], v[38:41]
	v_mfma_f32_16x16x32_bf16 v[34:37], v[200:203], v[216:219], v[34:37]
	v_mfma_f32_16x16x32_bf16 v[22:25], v[192:195], v[224:227], v[22:25]
	v_mfma_f32_16x16x32_bf16 v[18:21], v[200:203], v[224:227], v[18:21]
	v_mfma_f32_16x16x32_bf16 v[6:9], v[192:195], v[236:239], v[6:9]
	v_mfma_f32_16x16x32_bf16 v[2:5], v[200:203], v[236:239], v[2:5]
	s_barrier
	s_setprio 0
	s_add_i32 s69, 0, 0x18000
	v_add_u32_e32 v139, s69, v161
	s_add_i32 s70, 0, 0x1c000
	ds_read_b128 v[148:151], v139
	ds_read_b128 v[174:177], v139 offset:1024
	ds_read_b128 v[180:183], v139 offset:2048
	ds_read_b128 v[184:187], v139 offset:3072
	v_add_u32_e32 v139, s70, v161
	ds_read_b128 v[188:191], v139
	ds_read_b128 v[192:195], v139 offset:1024
	ds_read_b128 v[196:199], v139 offset:2048
	ds_read_b128 v[200:203], v139 offset:3072
	s_add_u32 s52, s52, 0x100000
	s_addc_u32 s53, s53, 0
	s_mov_b32 m0, s41
	v_lshl_add_u64 v[170:171], s[52:53], 0, v[130:131]
	ds_read_b128 v[204:207], v173 offset:32768
	ds_read_b128 v[208:211], v173 offset:33792
	ds_read_b128 v[212:215], v173 offset:34816
	ds_read_b128 v[216:219], v173 offset:35840
	ds_read_b128 v[220:223], v173 offset:36864
	ds_read_b128 v[224:227], v173 offset:37888
	ds_read_b128 v[228:231], v173 offset:38912
	ds_read_b128 v[236:239], v173 offset:39936
	global_load_lds_dwordx4 v[170:171], off
	v_lshl_add_u64 v[170:171], s[52:53], 0, v[134:135]
	s_mov_b32 m0, s43
	s_nop 0
	global_load_lds_dwordx4 v[170:171], off
	s_setprio 1
	s_waitcnt vmcnt(8) lgkmcnt(0)
	s_barrier
	v_mfma_f32_16x16x32_bf16 v[126:129], v[148:151], v[204:207], v[126:129]
	v_mfma_f32_16x16x32_bf16 v[122:125], v[180:183], v[204:207], v[122:125]
	v_mfma_f32_16x16x32_bf16 v[110:113], v[148:151], v[212:215], v[110:113]
	v_mfma_f32_16x16x32_bf16 v[106:109], v[180:183], v[212:215], v[106:109]
	v_mfma_f32_16x16x32_bf16 v[94:97], v[148:151], v[220:223], v[94:97]
	v_mfma_f32_16x16x32_bf16 v[90:93], v[180:183], v[220:223], v[90:93]
	v_mfma_f32_16x16x32_bf16 v[78:81], v[148:151], v[228:231], v[78:81]
	v_mfma_f32_16x16x32_bf16 v[74:77], v[180:183], v[228:231], v[74:77]
	v_mfma_f32_16x16x32_bf16 v[126:129], v[174:177], v[208:211], v[126:129]
	v_mfma_f32_16x16x32_bf16 v[122:125], v[184:187], v[208:211], v[122:125]
	v_mfma_f32_16x16x32_bf16 v[110:113], v[174:177], v[216:219], v[110:113]
	v_mfma_f32_16x16x32_bf16 v[106:109], v[184:187], v[216:219], v[106:109]
	v_mfma_f32_16x16x32_bf16 v[94:97], v[174:177], v[224:227], v[94:97]
	v_mfma_f32_16x16x32_bf16 v[90:93], v[184:187], v[224:227], v[90:93]
	v_mfma_f32_16x16x32_bf16 v[78:81], v[174:177], v[236:239], v[78:81]
	v_mfma_f32_16x16x32_bf16 v[74:77], v[184:187], v[236:239], v[74:77]
	v_mfma_f32_16x16x32_bf16 v[118:121], v[188:191], v[204:207], v[118:121]
	v_mfma_f32_16x16x32_bf16 v[114:117], v[196:199], v[204:207], v[114:117]
	v_mfma_f32_16x16x32_bf16 v[102:105], v[188:191], v[212:215], v[102:105]
	v_mfma_f32_16x16x32_bf16 v[98:101], v[196:199], v[212:215], v[98:101]
	v_mfma_f32_16x16x32_bf16 v[86:89], v[188:191], v[220:223], v[86:89]
	v_mfma_f32_16x16x32_bf16 v[82:85], v[196:199], v[220:223], v[82:85]
	v_mfma_f32_16x16x32_bf16 v[70:73], v[188:191], v[228:231], v[70:73]
	v_mfma_f32_16x16x32_bf16 v[66:69], v[196:199], v[228:231], v[66:69]
	v_mfma_f32_16x16x32_bf16 v[118:121], v[192:195], v[208:211], v[118:121]
	v_mfma_f32_16x16x32_bf16 v[114:117], v[200:203], v[208:211], v[114:117]
	v_mfma_f32_16x16x32_bf16 v[102:105], v[192:195], v[216:219], v[102:105]
	v_mfma_f32_16x16x32_bf16 v[98:101], v[200:203], v[216:219], v[98:101]
	v_mfma_f32_16x16x32_bf16 v[86:89], v[192:195], v[224:227], v[86:89]
	v_mfma_f32_16x16x32_bf16 v[82:85], v[200:203], v[224:227], v[82:85]
	v_mfma_f32_16x16x32_bf16 v[70:73], v[192:195], v[236:239], v[70:73]
	v_mfma_f32_16x16x32_bf16 v[66:69], v[200:203], v[236:239], v[66:69]
	s_barrier
	s_setprio 0
	s_add_i32 s52, s69, s35
	v_lshl_add_u64 v[154:155], v[154:155], 0, s[16:17]
	s_mov_b32 m0, s52
	ds_read_b128 v[204:207], v173 offset:49152
	ds_read_b128 v[208:211], v173 offset:50176
	ds_read_b128 v[212:215], v173 offset:51200
	ds_read_b128 v[216:219], v173 offset:52224
	ds_read_b128 v[220:223], v173 offset:53248
	ds_read_b128 v[224:227], v173 offset:54272
	ds_read_b128 v[228:231], v173 offset:55296
	ds_read_b128 v[236:239], v173 offset:56320
	global_load_lds_dwordx4 v[154:155], off
	s_add_i32 m0, s52, 0x2000
	s_add_u32 s50, s50, 0x100080
	v_lshl_add_u64 v[154:155], v[158:159], 0, s[16:17]
	s_addc_u32 s51, s51, 0
	s_add_i32 s52, s70, s35
	global_load_lds_dwordx4 v[154:155], off
	v_lshl_add_u64 v[154:155], s[50:51], 0, v[132:133]
	s_mov_b32 m0, s52
	s_nop 0
	global_load_lds_dwordx4 v[154:155], off
	v_lshl_add_u64 v[154:155], s[50:51], 0, v[136:137]
	s_add_i32 m0, s52, 0x2000
	s_nop 0
	global_load_lds_dwordx4 v[154:155], off
	v_lshl_add_u64 v[154:155], v[162:163], 0, s[16:17]
	s_mov_b32 m0, s57
	s_nop 0
	global_load_lds_dwordx4 v[154:155], off
	v_lshl_add_u64 v[154:155], v[166:167], 0, s[16:17]
	s_mov_b32 m0, s58
	s_nop 0
	global_load_lds_dwordx4 v[154:155], off
	s_setprio 1
	s_waitcnt vmcnt(8) lgkmcnt(0)
	s_barrier
	v_mfma_f32_16x16x32_bf16 v[62:65], v[148:151], v[204:207], v[62:65]
	v_mfma_f32_16x16x32_bf16 v[58:61], v[180:183], v[204:207], v[58:61]
	v_mfma_f32_16x16x32_bf16 v[46:49], v[148:151], v[212:215], v[46:49]
	v_mfma_f32_16x16x32_bf16 v[42:45], v[180:183], v[212:215], v[42:45]
	v_mfma_f32_16x16x32_bf16 v[30:33], v[148:151], v[220:223], v[30:33]
	v_mfma_f32_16x16x32_bf16 v[26:29], v[180:183], v[220:223], v[26:29]
	v_mfma_f32_16x16x32_bf16 v[14:17], v[148:151], v[228:231], v[14:17]
	v_mfma_f32_16x16x32_bf16 v[10:13], v[180:183], v[228:231], v[10:13]
	v_mfma_f32_16x16x32_bf16 v[62:65], v[174:177], v[208:211], v[62:65]
	v_mfma_f32_16x16x32_bf16 v[58:61], v[184:187], v[208:211], v[58:61]
	v_mfma_f32_16x16x32_bf16 v[46:49], v[174:177], v[216:219], v[46:49]
	v_mfma_f32_16x16x32_bf16 v[42:45], v[184:187], v[216:219], v[42:45]
	v_mfma_f32_16x16x32_bf16 v[30:33], v[174:177], v[224:227], v[30:33]
	v_mfma_f32_16x16x32_bf16 v[26:29], v[184:187], v[224:227], v[26:29]
	v_mfma_f32_16x16x32_bf16 v[14:17], v[174:177], v[236:239], v[14:17]
	v_mfma_f32_16x16x32_bf16 v[10:13], v[184:187], v[236:239], v[10:13]
	v_mfma_f32_16x16x32_bf16 v[54:57], v[188:191], v[204:207], v[54:57]
	v_mfma_f32_16x16x32_bf16 v[50:53], v[196:199], v[204:207], v[50:53]
	v_mfma_f32_16x16x32_bf16 v[38:41], v[188:191], v[212:215], v[38:41]
	v_mfma_f32_16x16x32_bf16 v[34:37], v[196:199], v[212:215], v[34:37]
	v_mfma_f32_16x16x32_bf16 v[22:25], v[188:191], v[220:223], v[22:25]
	v_mfma_f32_16x16x32_bf16 v[18:21], v[196:199], v[220:223], v[18:21]
	v_mfma_f32_16x16x32_bf16 v[6:9], v[188:191], v[228:231], v[6:9]
	v_mfma_f32_16x16x32_bf16 v[2:5], v[196:199], v[228:231], v[2:5]
	v_mfma_f32_16x16x32_bf16 v[54:57], v[192:195], v[208:211], v[54:57]
	v_mfma_f32_16x16x32_bf16 v[50:53], v[200:203], v[208:211], v[50:53]
	v_mfma_f32_16x16x32_bf16 v[38:41], v[192:195], v[216:219], v[38:41]
	v_mfma_f32_16x16x32_bf16 v[34:37], v[200:203], v[216:219], v[34:37]
	v_mfma_f32_16x16x32_bf16 v[22:25], v[192:195], v[224:227], v[22:25]
	v_mfma_f32_16x16x32_bf16 v[18:21], v[200:203], v[224:227], v[18:21]
	v_mfma_f32_16x16x32_bf16 v[6:9], v[192:195], v[236:239], v[6:9]
	v_mfma_f32_16x16x32_bf16 v[2:5], v[200:203], v[236:239], v[2:5]
	s_barrier
	s_setprio 0
	s_add_i32 s68, s68, 2
	s_add_u32 s4, s4, 0x100
	s_addc_u32 s5, s5, 0
	s_add_u32 s63, s63, 0x100
	s_addc_u32 s65, s65, 0
	s_cmp_gt_u32 s68, 61
	s_cbranch_scc0 .LBB0_446
	s_and_b64 vcc, exec, s[20:21]
	s_cbranch_vccz .LBB0_449
	s_barrier

.LBB0_668:
	ds_read_b128 v[154:157], v151
	ds_read_b128 v[158:161], v151 offset:1024
	ds_read_b128 v[162:165], v151 offset:2048
	ds_read_b128 v[166:169], v151 offset:3072
	ds_read_b128 v[170:173], v152
	ds_read_b128 v[174:177], v152 offset:1024
	ds_read_b128 v[178:181], v152 offset:2048
	ds_read_b128 v[182:185], v152 offset:3072
	s_add_u32 s36, s34, 0xfff00080
	s_addc_u32 s37, s35, -1
	s_cmp_eq_u32 s68, 60
	s_cselect_b32 s39, s25, s37
	s_cselect_b32 s38, s61, s36
	s_cselect_b32 s37, s23, s65
	s_cselect_b32 s36, s62, s63
	v_lshl_add_u64 v[148:149], s[34:35], 0, v[140:141]
	s_add_i32 m0, s31, 0xc000
	ds_read_b128 v[186:189], v153
	ds_read_b128 v[190:193], v153 offset:1024
	ds_read_b128 v[194:197], v153 offset:2048
	ds_read_b128 v[198:201], v153 offset:3072
	ds_read_b128 v[202:205], v153 offset:4096
	ds_read_b128 v[206:209], v153 offset:5120
	ds_read_b128 v[210:213], v153 offset:6144
	ds_read_b128 v[214:217], v153 offset:7168
	global_load_lds_dwordx4 v[148:149], off
	v_lshl_add_u64 v[148:149], s[34:35], 0, v[142:143]
	s_add_i32 m0, s31, 0xe000
	s_nop 0
	global_load_lds_dwordx4 v[148:149], off
	s_setprio 1
	s_waitcnt vmcnt(8) lgkmcnt(0)
	s_barrier
	v_mfma_f32_16x16x32_bf16 v[126:129], v[154:157], v[186:189], v[126:129]
	v_mfma_f32_16x16x32_bf16 v[122:125], v[162:165], v[186:189], v[122:125]
	v_mfma_f32_16x16x32_bf16 v[114:117], v[154:157], v[194:197], v[114:117]
	v_mfma_f32_16x16x32_bf16 v[106:109], v[162:165], v[194:197], v[106:109]
	v_mfma_f32_16x16x32_bf16 v[98:101], v[154:157], v[202:205], v[98:101]
	v_mfma_f32_16x16x32_bf16 v[90:93], v[162:165], v[202:205], v[90:93]
	v_mfma_f32_16x16x32_bf16 v[82:85], v[154:157], v[210:213], v[82:85]
	v_mfma_f32_16x16x32_bf16 v[74:77], v[162:165], v[210:213], v[74:77]
	v_mfma_f32_16x16x32_bf16 v[126:129], v[158:161], v[190:193], v[126:129]
	v_mfma_f32_16x16x32_bf16 v[122:125], v[166:169], v[190:193], v[122:125]
	v_mfma_f32_16x16x32_bf16 v[114:117], v[158:161], v[198:201], v[114:117]
	v_mfma_f32_16x16x32_bf16 v[106:109], v[166:169], v[198:201], v[106:109]
	v_mfma_f32_16x16x32_bf16 v[98:101], v[158:161], v[206:209], v[98:101]
	v_mfma_f32_16x16x32_bf16 v[90:93], v[166:169], v[206:209], v[90:93]
	v_mfma_f32_16x16x32_bf16 v[82:85], v[158:161], v[214:217], v[82:85]
	v_mfma_f32_16x16x32_bf16 v[74:77], v[166:169], v[214:217], v[74:77]
	v_mfma_f32_16x16x32_bf16 v[118:121], v[170:173], v[186:189], v[118:121]
	v_mfma_f32_16x16x32_bf16 v[110:113], v[178:181], v[186:189], v[110:113]
	v_mfma_f32_16x16x32_bf16 v[102:105], v[170:173], v[194:197], v[102:105]
	v_mfma_f32_16x16x32_bf16 v[94:97], v[178:181], v[194:197], v[94:97]
	v_mfma_f32_16x16x32_bf16 v[86:89], v[170:173], v[202:205], v[86:89]
	v_mfma_f32_16x16x32_bf16 v[78:81], v[178:181], v[202:205], v[78:81]
	v_mfma_f32_16x16x32_bf16 v[70:73], v[170:173], v[210:213], v[70:73]
	v_mfma_f32_16x16x32_bf16 v[66:69], v[178:181], v[210:213], v[66:69]
	v_mfma_f32_16x16x32_bf16 v[118:121], v[174:177], v[190:193], v[118:121]
	v_mfma_f32_16x16x32_bf16 v[110:113], v[182:185], v[190:193], v[110:113]
	v_mfma_f32_16x16x32_bf16 v[102:105], v[174:177], v[198:201], v[102:105]
	v_mfma_f32_16x16x32_bf16 v[94:97], v[182:185], v[198:201], v[94:97]
	v_mfma_f32_16x16x32_bf16 v[86:89], v[174:177], v[206:209], v[86:89]
	v_mfma_f32_16x16x32_bf16 v[78:81], v[182:185], v[206:209], v[78:81]
	v_mfma_f32_16x16x32_bf16 v[70:73], v[174:177], v[214:217], v[70:73]
	v_mfma_f32_16x16x32_bf16 v[66:69], v[182:185], v[214:217], v[66:69]
	s_barrier
	s_setprio 0
	s_add_i32 s69, s54, s47
	v_lshl_add_u64 v[148:149], s[36:37], 0, v[136:137]
	s_mov_b32 m0, s69
	ds_read_b128 v[186:189], v153 offset:16384
	ds_read_b128 v[190:193], v153 offset:17408
	ds_read_b128 v[194:197], v153 offset:18432
	ds_read_b128 v[198:201], v153 offset:19456
	ds_read_b128 v[202:205], v153 offset:20480
	ds_read_b128 v[206:209], v153 offset:21504
	ds_read_b128 v[210:213], v153 offset:22528
	ds_read_b128 v[214:217], v153 offset:23552
	global_load_lds_dwordx4 v[148:149], off
	s_add_i32 m0, s69, 0x2000
	s_add_u32 s70, s36, 0x100000
	v_lshl_add_u64 v[218:219], s[36:37], 0, v[132:133]
	s_addc_u32 s71, s37, 0
	s_add_i32 s69, s55, s47
	global_load_lds_dwordx4 v[218:219], off
	v_lshl_add_u64 v[220:221], s[70:71], 0, v[136:137]
	s_mov_b32 m0, s69
	v_lshl_add_u64 v[222:223], s[38:39], 0, v[134:135]
	global_load_lds_dwordx4 v[220:221], off
	v_lshl_add_u64 v[220:221], s[70:71], 0, v[132:133]
	s_add_i32 m0, s69, 0x2000
	s_nop 0
	global_load_lds_dwordx4 v[220:221], off
	v_lshl_add_u64 v[220:221], s[38:39], 0, v[138:139]
	s_mov_b32 m0, s31
	s_nop 0
	global_load_lds_dwordx4 v[220:221], off
	s_mov_b32 m0, s48
	s_nop 0
	global_load_lds_dwordx4 v[222:223], off
	s_setprio 1
	s_waitcnt vmcnt(8) lgkmcnt(0)
	s_barrier
	v_mfma_f32_16x16x32_bf16 v[62:65], v[154:157], v[186:189], v[62:65]
	v_mfma_f32_16x16x32_bf16 v[58:61], v[162:165], v[186:189], v[58:61]
	v_mfma_f32_16x16x32_bf16 v[50:53], v[154:157], v[194:197], v[50:53]
	v_mfma_f32_16x16x32_bf16 v[42:45], v[162:165], v[194:197], v[42:45]
	v_mfma_f32_16x16x32_bf16 v[34:37], v[154:157], v[202:205], v[34:37]
	v_mfma_f32_16x16x32_bf16 v[26:29], v[162:165], v[202:205], v[26:29]
	v_mfma_f32_16x16x32_bf16 v[18:21], v[154:157], v[210:213], v[18:21]
	v_mfma_f32_16x16x32_bf16 v[10:13], v[162:165], v[210:213], v[10:13]
	v_mfma_f32_16x16x32_bf16 v[62:65], v[158:161], v[190:193], v[62:65]
	v_mfma_f32_16x16x32_bf16 v[58:61], v[166:169], v[190:193], v[58:61]
	v_mfma_f32_16x16x32_bf16 v[50:53], v[158:161], v[198:201], v[50:53]
	v_mfma_f32_16x16x32_bf16 v[42:45], v[166:169], v[198:201], v[42:45]
	v_mfma_f32_16x16x32_bf16 v[34:37], v[158:161], v[206:209], v[34:37]
	v_mfma_f32_16x16x32_bf16 v[26:29], v[166:169], v[206:209], v[26:29]
	v_mfma_f32_16x16x32_bf16 v[18:21], v[158:161], v[214:217], v[18:21]
	v_mfma_f32_16x16x32_bf16 v[10:13], v[166:169], v[214:217], v[10:13]
	v_mfma_f32_16x16x32_bf16 v[54:57], v[170:173], v[186:189], v[54:57]
	v_mfma_f32_16x16x32_bf16 v[46:49], v[178:181], v[186:189], v[46:49]
	v_mfma_f32_16x16x32_bf16 v[38:41], v[170:173], v[194:197], v[38:41]
	v_mfma_f32_16x16x32_bf16 v[30:33], v[178:181], v[194:197], v[30:33]
	v_mfma_f32_16x16x32_bf16 v[22:25], v[170:173], v[202:205], v[22:25]
	v_mfma_f32_16x16x32_bf16 v[14:17], v[178:181], v[202:205], v[14:17]
	v_mfma_f32_16x16x32_bf16 v[6:9], v[170:173], v[210:213], v[6:9]
	v_mfma_f32_16x16x32_bf16 v[2:5], v[178:181], v[210:213], v[2:5]
	v_mfma_f32_16x16x32_bf16 v[54:57], v[174:177], v[190:193], v[54:57]
	v_mfma_f32_16x16x32_bf16 v[46:49], v[182:185], v[190:193], v[46:49]
	v_mfma_f32_16x16x32_bf16 v[38:41], v[174:177], v[198:201], v[38:41]
	v_mfma_f32_16x16x32_bf16 v[30:33], v[182:185], v[198:201], v[30:33]
	v_mfma_f32_16x16x32_bf16 v[22:25], v[174:177], v[206:209], v[22:25]
	v_mfma_f32_16x16x32_bf16 v[14:17], v[182:185], v[206:209], v[14:17]
	v_mfma_f32_16x16x32_bf16 v[6:9], v[174:177], v[214:217], v[6:9]
	v_mfma_f32_16x16x32_bf16 v[2:5], v[182:185], v[214:217], v[2:5]
	s_barrier
	s_setprio 0
	s_add_i32 s69, 0, 0x18000
	s_add_i32 s70, 0, 0x1c000
	v_add_u32_e32 v166, s69, v131
	v_add_u32_e32 v182, s70, v131
	ds_read_b128 v[154:157], v166
	ds_read_b128 v[158:161], v166 offset:1024
	ds_read_b128 v[162:165], v166 offset:2048
	ds_read_b128 v[166:169], v166 offset:3072
	ds_read_b128 v[170:173], v182
	ds_read_b128 v[174:177], v182 offset:1024
	ds_read_b128 v[178:181], v182 offset:2048
	ds_read_b128 v[182:185], v182 offset:3072
	s_add_u32 s38, s38, 0x100000
	s_addc_u32 s39, s39, 0
	s_mov_b32 m0, s49
	v_lshl_add_u64 v[224:225], s[38:39], 0, v[138:139]
	ds_read_b128 v[186:189], v153 offset:32768
	ds_read_b128 v[190:193], v153 offset:33792
	ds_read_b128 v[194:197], v153 offset:34816
	ds_read_b128 v[198:201], v153 offset:35840
	ds_read_b128 v[202:205], v153 offset:36864
	ds_read_b128 v[206:209], v153 offset:37888
	ds_read_b128 v[210:213], v153 offset:38912
	ds_read_b128 v[214:217], v153 offset:39936
	global_load_lds_dwordx4 v[224:225], off
	v_lshl_add_u64 v[224:225], s[38:39], 0, v[134:135]
	s_mov_b32 m0, s50
	s_nop 0
	global_load_lds_dwordx4 v[224:225], off
	s_setprio 1
	s_waitcnt vmcnt(8) lgkmcnt(0)
	s_barrier
	v_mfma_f32_16x16x32_bf16 v[126:129], v[154:157], v[186:189], v[126:129]
	v_mfma_f32_16x16x32_bf16 v[122:125], v[162:165], v[186:189], v[122:125]
	v_mfma_f32_16x16x32_bf16 v[114:117], v[154:157], v[194:197], v[114:117]
	v_mfma_f32_16x16x32_bf16 v[106:109], v[162:165], v[194:197], v[106:109]
	v_mfma_f32_16x16x32_bf16 v[98:101], v[154:157], v[202:205], v[98:101]
	v_mfma_f32_16x16x32_bf16 v[90:93], v[162:165], v[202:205], v[90:93]
	v_mfma_f32_16x16x32_bf16 v[82:85], v[154:157], v[210:213], v[82:85]
	v_mfma_f32_16x16x32_bf16 v[74:77], v[162:165], v[210:213], v[74:77]
	v_mfma_f32_16x16x32_bf16 v[126:129], v[158:161], v[190:193], v[126:129]
	v_mfma_f32_16x16x32_bf16 v[122:125], v[166:169], v[190:193], v[122:125]
	v_mfma_f32_16x16x32_bf16 v[114:117], v[158:161], v[198:201], v[114:117]
	v_mfma_f32_16x16x32_bf16 v[106:109], v[166:169], v[198:201], v[106:109]
	v_mfma_f32_16x16x32_bf16 v[98:101], v[158:161], v[206:209], v[98:101]
	v_mfma_f32_16x16x32_bf16 v[90:93], v[166:169], v[206:209], v[90:93]
	v_mfma_f32_16x16x32_bf16 v[82:85], v[158:161], v[214:217], v[82:85]
	v_mfma_f32_16x16x32_bf16 v[74:77], v[166:169], v[214:217], v[74:77]
	v_mfma_f32_16x16x32_bf16 v[118:121], v[170:173], v[186:189], v[118:121]
	v_mfma_f32_16x16x32_bf16 v[110:113], v[178:181], v[186:189], v[110:113]
	v_mfma_f32_16x16x32_bf16 v[102:105], v[170:173], v[194:197], v[102:105]
	v_mfma_f32_16x16x32_bf16 v[94:97], v[178:181], v[194:197], v[94:97]
	v_mfma_f32_16x16x32_bf16 v[86:89], v[170:173], v[202:205], v[86:89]
	v_mfma_f32_16x16x32_bf16 v[78:81], v[178:181], v[202:205], v[78:81]
	v_mfma_f32_16x16x32_bf16 v[70:73], v[170:173], v[210:213], v[70:73]
	v_mfma_f32_16x16x32_bf16 v[66:69], v[178:181], v[210:213], v[66:69]
	v_mfma_f32_16x16x32_bf16 v[118:121], v[174:177], v[190:193], v[118:121]
	v_mfma_f32_16x16x32_bf16 v[110:113], v[182:185], v[190:193], v[110:113]
	v_mfma_f32_16x16x32_bf16 v[102:105], v[174:177], v[198:201], v[102:105]
	v_mfma_f32_16x16x32_bf16 v[94:97], v[182:185], v[198:201], v[94:97]
	v_mfma_f32_16x16x32_bf16 v[86:89], v[174:177], v[206:209], v[86:89]
	v_mfma_f32_16x16x32_bf16 v[78:81], v[182:185], v[206:209], v[78:81]
	v_mfma_f32_16x16x32_bf16 v[70:73], v[174:177], v[214:217], v[70:73]
	v_mfma_f32_16x16x32_bf16 v[66:69], v[182:185], v[214:217], v[66:69]
	s_barrier
	s_setprio 0
	s_add_i32 s38, s69, s47
	v_lshl_add_u64 v[148:149], v[148:149], 0, s[8:9]
	s_mov_b32 m0, s38
	ds_read_b128 v[186:189], v153 offset:49152
	ds_read_b128 v[190:193], v153 offset:50176
	ds_read_b128 v[194:197], v153 offset:51200
	ds_read_b128 v[198:201], v153 offset:52224
	ds_read_b128 v[202:205], v153 offset:53248
	ds_read_b128 v[206:209], v153 offset:54272
	ds_read_b128 v[210:213], v153 offset:55296
	ds_read_b128 v[214:217], v153 offset:56320
	global_load_lds_dwordx4 v[148:149], off
	s_add_i32 m0, s38, 0x2000
	s_add_u32 s36, s36, 0x100080
	v_lshl_add_u64 v[148:149], v[218:219], 0, s[8:9]
	s_addc_u32 s37, s37, 0
	s_add_i32 s38, s70, s47
	global_load_lds_dwordx4 v[148:149], off
	v_lshl_add_u64 v[148:149], s[36:37], 0, v[136:137]
	s_mov_b32 m0, s38
	s_nop 0
	global_load_lds_dwordx4 v[148:149], off
	v_lshl_add_u64 v[148:149], s[36:37], 0, v[132:133]
	s_add_i32 m0, s38, 0x2000
	s_nop 0
	global_load_lds_dwordx4 v[148:149], off
	v_lshl_add_u64 v[148:149], v[220:221], 0, s[8:9]
	s_mov_b32 m0, s52
	s_nop 0
	global_load_lds_dwordx4 v[148:149], off
	v_lshl_add_u64 v[148:149], v[222:223], 0, s[8:9]
	s_mov_b32 m0, s53
	s_nop 0
	global_load_lds_dwordx4 v[148:149], off
	s_setprio 1
	s_waitcnt vmcnt(8) lgkmcnt(0)
	s_barrier
	v_mfma_f32_16x16x32_bf16 v[62:65], v[154:157], v[186:189], v[62:65]
	v_mfma_f32_16x16x32_bf16 v[58:61], v[162:165], v[186:189], v[58:61]
	v_mfma_f32_16x16x32_bf16 v[50:53], v[154:157], v[194:197], v[50:53]
	v_mfma_f32_16x16x32_bf16 v[42:45], v[162:165], v[194:197], v[42:45]
	v_mfma_f32_16x16x32_bf16 v[34:37], v[154:157], v[202:205], v[34:37]
	v_mfma_f32_16x16x32_bf16 v[26:29], v[162:165], v[202:205], v[26:29]
	v_mfma_f32_16x16x32_bf16 v[18:21], v[154:157], v[210:213], v[18:21]
	v_mfma_f32_16x16x32_bf16 v[10:13], v[162:165], v[210:213], v[10:13]
	v_mfma_f32_16x16x32_bf16 v[62:65], v[158:161], v[190:193], v[62:65]
	v_mfma_f32_16x16x32_bf16 v[58:61], v[166:169], v[190:193], v[58:61]
	v_mfma_f32_16x16x32_bf16 v[50:53], v[158:161], v[198:201], v[50:53]
	v_mfma_f32_16x16x32_bf16 v[42:45], v[166:169], v[198:201], v[42:45]
	v_mfma_f32_16x16x32_bf16 v[34:37], v[158:161], v[206:209], v[34:37]
	v_mfma_f32_16x16x32_bf16 v[26:29], v[166:169], v[206:209], v[26:29]
	v_mfma_f32_16x16x32_bf16 v[18:21], v[158:161], v[214:217], v[18:21]
	v_mfma_f32_16x16x32_bf16 v[10:13], v[166:169], v[214:217], v[10:13]
	v_mfma_f32_16x16x32_bf16 v[54:57], v[170:173], v[186:189], v[54:57]
	v_mfma_f32_16x16x32_bf16 v[46:49], v[178:181], v[186:189], v[46:49]
	v_mfma_f32_16x16x32_bf16 v[38:41], v[170:173], v[194:197], v[38:41]
	v_mfma_f32_16x16x32_bf16 v[30:33], v[178:181], v[194:197], v[30:33]
	v_mfma_f32_16x16x32_bf16 v[22:25], v[170:173], v[202:205], v[22:25]
	v_mfma_f32_16x16x32_bf16 v[14:17], v[178:181], v[202:205], v[14:17]
	v_mfma_f32_16x16x32_bf16 v[6:9], v[170:173], v[210:213], v[6:9]
	v_mfma_f32_16x16x32_bf16 v[2:5], v[178:181], v[210:213], v[2:5]
	v_mfma_f32_16x16x32_bf16 v[54:57], v[174:177], v[190:193], v[54:57]
	v_mfma_f32_16x16x32_bf16 v[46:49], v[182:185], v[190:193], v[46:49]
	v_mfma_f32_16x16x32_bf16 v[38:41], v[174:177], v[198:201], v[38:41]
	v_mfma_f32_16x16x32_bf16 v[30:33], v[182:185], v[198:201], v[30:33]
	v_mfma_f32_16x16x32_bf16 v[22:25], v[174:177], v[206:209], v[22:25]
	v_mfma_f32_16x16x32_bf16 v[14:17], v[182:185], v[206:209], v[14:17]
	v_mfma_f32_16x16x32_bf16 v[6:9], v[174:177], v[214:217], v[6:9]
	v_mfma_f32_16x16x32_bf16 v[2:5], v[182:185], v[214:217], v[2:5]
	s_barrier
	s_setprio 0
	s_add_i32 s68, s68, 2
	s_add_u32 s34, s34, 0x100
	s_addc_u32 s35, s35, 0
	s_add_u32 s63, s63, 0x100
	s_addc_u32 s65, s65, 0
	s_cmp_gt_u32 s68, 61
	s_cbranch_scc0 .LBB0_668
	s_and_b64 vcc, exec, s[12:13]
	s_cbranch_vccz .LBB0_671
	s_barrier

.LBB0_845:
	ds_read_b128 v[130:133], v238
	ds_read_b128 v[134:137], v238 offset:1024
	ds_read_b128 v[138:141], v238 offset:2048
	ds_read_b128 v[142:145], v238 offset:3072
	ds_read_b128 v[146:149], v239
	ds_read_b128 v[150:153], v239 offset:1024
	ds_read_b128 v[154:157], v239 offset:2048
	ds_read_b128 v[158:161], v239 offset:3072
	s_add_u32 s56, s2, 0x100
	s_addc_u32 s57, s3, 0
	s_cmp_eq_u32 s92, 28
	s_cselect_b32 s61, s49, s57
	s_cselect_b32 s60, s88, s56
	s_cselect_b32 s59, s47, s91
	s_cselect_b32 s58, s89, s90
	v_lshl_add_u64 v[194:195], s[2:3], 0, v[210:211]
	s_add_i32 m0, s55, 0xc000
	ds_read_b128 v[162:165], v240
	ds_read_b128 v[166:169], v240 offset:1024
	ds_read_b128 v[170:173], v240 offset:2048
	ds_read_b128 v[174:177], v240 offset:3072
	ds_read_b128 v[178:181], v240 offset:4096
	ds_read_b128 v[182:185], v240 offset:5120
	ds_read_b128 v[186:189], v240 offset:6144
	ds_read_b128 v[190:193], v240 offset:7168
	global_load_lds_dwordx4 v[194:195], off
	v_lshl_add_u64 v[194:195], s[2:3], 0, v[212:213]
	s_add_i32 m0, s55, 0xe000
	s_nop 0
	global_load_lds_dwordx4 v[194:195], off
	s_setprio 1
	s_waitcnt vmcnt(8) lgkmcnt(0)
	s_barrier
	v_mfma_i32_16x16x64_i8 v[126:129], v[130:133], v[162:165], v[126:129]
	v_mfma_i32_16x16x64_i8 v[122:125], v[138:141], v[162:165], v[122:125]
	v_mfma_i32_16x16x64_i8 v[118:121], v[130:133], v[170:173], v[118:121]
	v_mfma_i32_16x16x64_i8 v[110:113], v[138:141], v[170:173], v[110:113]
	v_mfma_i32_16x16x64_i8 v[78:81], v[130:133], v[178:181], v[78:81]
	v_mfma_i32_16x16x64_i8 v[30:33], v[138:141], v[178:181], v[30:33]
	v_mfma_i32_16x16x64_i8 v[74:77], v[130:133], v[186:189], v[74:77]
	v_mfma_i32_16x16x64_i8 v[26:29], v[138:141], v[186:189], v[26:29]
	v_mfma_i32_16x16x64_i8 v[126:129], v[134:137], v[166:169], v[126:129]
	v_mfma_i32_16x16x64_i8 v[122:125], v[142:145], v[166:169], v[122:125]
	v_mfma_i32_16x16x64_i8 v[118:121], v[134:137], v[174:177], v[118:121]
	v_mfma_i32_16x16x64_i8 v[110:113], v[142:145], v[174:177], v[110:113]
	v_mfma_i32_16x16x64_i8 v[78:81], v[134:137], v[182:185], v[78:81]
	v_mfma_i32_16x16x64_i8 v[30:33], v[142:145], v[182:185], v[30:33]
	v_mfma_i32_16x16x64_i8 v[74:77], v[134:137], v[190:193], v[74:77]
	v_mfma_i32_16x16x64_i8 v[26:29], v[142:145], v[190:193], v[26:29]
	v_mfma_i32_16x16x64_i8 v[102:105], v[146:149], v[162:165], v[102:105]
	v_mfma_i32_16x16x64_i8 v[98:101], v[154:157], v[162:165], v[98:101]
	v_mfma_i32_16x16x64_i8 v[94:97], v[146:149], v[170:173], v[94:97]
	v_mfma_i32_16x16x64_i8 v[90:93], v[154:157], v[170:173], v[90:93]
	v_mfma_i32_16x16x64_i8 v[70:73], v[146:149], v[178:181], v[70:73]
	v_mfma_i32_16x16x64_i8 v[22:25], v[154:157], v[178:181], v[22:25]
	v_mfma_i32_16x16x64_i8 v[66:69], v[146:149], v[186:189], v[66:69]
	v_mfma_i32_16x16x64_i8 v[18:21], v[154:157], v[186:189], v[18:21]
	v_mfma_i32_16x16x64_i8 v[102:105], v[150:153], v[166:169], v[102:105]
	v_mfma_i32_16x16x64_i8 v[98:101], v[158:161], v[166:169], v[98:101]
	v_mfma_i32_16x16x64_i8 v[94:97], v[150:153], v[174:177], v[94:97]
	v_mfma_i32_16x16x64_i8 v[90:93], v[158:161], v[174:177], v[90:93]
	v_mfma_i32_16x16x64_i8 v[70:73], v[150:153], v[182:185], v[70:73]
	v_mfma_i32_16x16x64_i8 v[22:25], v[158:161], v[182:185], v[22:25]
	v_mfma_i32_16x16x64_i8 v[66:69], v[150:153], v[190:193], v[66:69]
	v_mfma_i32_16x16x64_i8 v[18:21], v[158:161], v[190:193], v[18:21]
	s_barrier
	s_setprio 0
	s_add_i32 s2, s84, s65
	v_lshl_add_u64 v[194:195], s[58:59], 0, v[206:207]
	s_mov_b32 m0, s2
	ds_read_b128 v[162:165], v240 offset:16384
	ds_read_b128 v[166:169], v240 offset:17408
	ds_read_b128 v[170:173], v240 offset:18432
	ds_read_b128 v[174:177], v240 offset:19456
	ds_read_b128 v[178:181], v240 offset:20480
	ds_read_b128 v[182:185], v240 offset:21504
	ds_read_b128 v[186:189], v240 offset:22528
	ds_read_b128 v[190:193], v240 offset:23552
	global_load_lds_dwordx4 v[194:195], off
	s_add_i32 m0, s2, 0x2000
	s_add_u32 s2, s58, 0x80000
	v_lshl_add_u64 v[196:197], s[58:59], 0, v[202:203]
	s_addc_u32 s3, s59, 0
	s_add_i32 s93, s85, s65
	global_load_lds_dwordx4 v[196:197], off
	v_lshl_add_u64 v[198:199], s[2:3], 0, v[206:207]
	s_mov_b32 m0, s93
	v_lshl_add_u64 v[200:201], s[60:61], 0, v[204:205]
	global_load_lds_dwordx4 v[198:199], off
	v_lshl_add_u64 v[198:199], s[2:3], 0, v[202:203]
	s_add_i32 m0, s93, 0x2000
	s_nop 0
	global_load_lds_dwordx4 v[198:199], off
	v_lshl_add_u64 v[198:199], s[60:61], 0, v[208:209]
	s_mov_b32 m0, s55
	s_nop 0
	global_load_lds_dwordx4 v[198:199], off
	s_mov_b32 m0, s69
	s_nop 0
	global_load_lds_dwordx4 v[200:201], off
	s_setprio 1
	s_waitcnt vmcnt(8) lgkmcnt(0)
	s_barrier
	v_mfma_i32_16x16x64_i8 v[62:65], v[130:133], v[162:165], v[62:65]
	v_mfma_i32_16x16x64_i8 v[14:17], v[138:141], v[162:165], v[14:17]
	v_mfma_i32_16x16x64_i8 v[58:61], v[130:133], v[170:173], v[58:61]
	v_mfma_i32_16x16x64_i8 v[10:13], v[138:141], v[170:173], v[10:13]
	v_mfma_i32_16x16x64_i8 v[114:117], v[130:133], v[178:181], v[114:117]
	v_mfma_i32_16x16x64_i8 v[106:109], v[138:141], v[178:181], v[106:109]
	v_mfma_i32_16x16x64_i8 v[86:89], v[130:133], v[186:189], v[86:89]
	v_mfma_i32_16x16x64_i8 v[82:85], v[138:141], v[186:189], v[82:85]
	v_mfma_i32_16x16x64_i8 v[62:65], v[134:137], v[166:169], v[62:65]
	v_mfma_i32_16x16x64_i8 v[14:17], v[142:145], v[166:169], v[14:17]
	v_mfma_i32_16x16x64_i8 v[58:61], v[134:137], v[174:177], v[58:61]
	v_mfma_i32_16x16x64_i8 v[10:13], v[142:145], v[174:177], v[10:13]
	v_mfma_i32_16x16x64_i8 v[114:117], v[134:137], v[182:185], v[114:117]
	v_mfma_i32_16x16x64_i8 v[106:109], v[142:145], v[182:185], v[106:109]
	v_mfma_i32_16x16x64_i8 v[86:89], v[134:137], v[190:193], v[86:89]
	v_mfma_i32_16x16x64_i8 v[82:85], v[142:145], v[190:193], v[82:85]
	v_mfma_i32_16x16x64_i8 v[50:53], v[146:149], v[162:165], v[50:53]
	v_mfma_i32_16x16x64_i8 v[6:9], v[154:157], v[162:165], v[6:9]
	v_mfma_i32_16x16x64_i8 v[42:45], v[146:149], v[170:173], v[42:45]
	v_mfma_i32_16x16x64_i8 v[2:5], v[154:157], v[170:173], v[2:5]
	v_mfma_i32_16x16x64_i8 v[54:57], v[146:149], v[178:181], v[54:57]
	v_mfma_i32_16x16x64_i8 v[46:49], v[154:157], v[178:181], v[46:49]
	v_mfma_i32_16x16x64_i8 v[38:41], v[146:149], v[186:189], v[38:41]
	v_mfma_i32_16x16x64_i8 v[34:37], v[154:157], v[186:189], v[34:37]
	v_mfma_i32_16x16x64_i8 v[50:53], v[150:153], v[166:169], v[50:53]
	v_mfma_i32_16x16x64_i8 v[6:9], v[158:161], v[166:169], v[6:9]
	v_mfma_i32_16x16x64_i8 v[42:45], v[150:153], v[174:177], v[42:45]
	v_mfma_i32_16x16x64_i8 v[2:5], v[158:161], v[174:177], v[2:5]
	v_mfma_i32_16x16x64_i8 v[54:57], v[150:153], v[182:185], v[54:57]
	v_mfma_i32_16x16x64_i8 v[46:49], v[158:161], v[182:185], v[46:49]
	v_mfma_i32_16x16x64_i8 v[38:41], v[150:153], v[190:193], v[38:41]
	v_mfma_i32_16x16x64_i8 v[34:37], v[158:161], v[190:193], v[34:37]
	s_barrier
	s_setprio 0
	s_add_i32 s93, 0, 0x18000
	s_add_i32 s94, 0, 0x1c000
	v_add_u32_e32 v142, s93, v237
	v_add_u32_e32 v158, s94, v237
	ds_read_b128 v[130:133], v142
	ds_read_b128 v[134:137], v142 offset:1024
	ds_read_b128 v[138:141], v142 offset:2048
	ds_read_b128 v[142:145], v142 offset:3072
	ds_read_b128 v[146:149], v158
	ds_read_b128 v[150:153], v158 offset:1024
	ds_read_b128 v[154:157], v158 offset:2048
	ds_read_b128 v[158:161], v158 offset:3072
	s_add_u32 s2, s60, 0x4000
	s_addc_u32 s3, s61, 0
	s_mov_b32 m0, s70
	v_lshl_add_u64 v[220:221], s[2:3], 0, v[208:209]
	ds_read_b128 v[162:165], v240 offset:32768
	ds_read_b128 v[166:169], v240 offset:33792
	ds_read_b128 v[170:173], v240 offset:34816
	ds_read_b128 v[174:177], v240 offset:35840
	ds_read_b128 v[178:181], v240 offset:36864
	ds_read_b128 v[182:185], v240 offset:37888
	ds_read_b128 v[186:189], v240 offset:38912
	ds_read_b128 v[190:193], v240 offset:39936
	global_load_lds_dwordx4 v[220:221], off
	v_lshl_add_u64 v[220:221], s[2:3], 0, v[204:205]
	s_mov_b32 m0, s71
	s_nop 0
	global_load_lds_dwordx4 v[220:221], off
	s_setprio 1
	s_waitcnt vmcnt(8) lgkmcnt(0)
	s_barrier
	v_mfma_i32_16x16x64_i8 v[126:129], v[130:133], v[162:165], v[126:129]
	v_mfma_i32_16x16x64_i8 v[122:125], v[138:141], v[162:165], v[122:125]
	v_mfma_i32_16x16x64_i8 v[118:121], v[130:133], v[170:173], v[118:121]
	v_mfma_i32_16x16x64_i8 v[110:113], v[138:141], v[170:173], v[110:113]
	v_mfma_i32_16x16x64_i8 v[78:81], v[130:133], v[178:181], v[78:81]
	v_mfma_i32_16x16x64_i8 v[30:33], v[138:141], v[178:181], v[30:33]
	v_mfma_i32_16x16x64_i8 v[74:77], v[130:133], v[186:189], v[74:77]
	v_mfma_i32_16x16x64_i8 v[26:29], v[138:141], v[186:189], v[26:29]
	v_mfma_i32_16x16x64_i8 v[126:129], v[134:137], v[166:169], v[126:129]
	v_mfma_i32_16x16x64_i8 v[122:125], v[142:145], v[166:169], v[122:125]
	v_mfma_i32_16x16x64_i8 v[118:121], v[134:137], v[174:177], v[118:121]
	v_mfma_i32_16x16x64_i8 v[110:113], v[142:145], v[174:177], v[110:113]
	v_mfma_i32_16x16x64_i8 v[78:81], v[134:137], v[182:185], v[78:81]
	v_mfma_i32_16x16x64_i8 v[30:33], v[142:145], v[182:185], v[30:33]
	v_mfma_i32_16x16x64_i8 v[74:77], v[134:137], v[190:193], v[74:77]
	v_mfma_i32_16x16x64_i8 v[26:29], v[142:145], v[190:193], v[26:29]
	v_mfma_i32_16x16x64_i8 v[102:105], v[146:149], v[162:165], v[102:105]
	v_mfma_i32_16x16x64_i8 v[98:101], v[154:157], v[162:165], v[98:101]
	v_mfma_i32_16x16x64_i8 v[94:97], v[146:149], v[170:173], v[94:97]
	v_mfma_i32_16x16x64_i8 v[90:93], v[154:157], v[170:173], v[90:93]
	v_mfma_i32_16x16x64_i8 v[70:73], v[146:149], v[178:181], v[70:73]
	v_mfma_i32_16x16x64_i8 v[22:25], v[154:157], v[178:181], v[22:25]
	v_mfma_i32_16x16x64_i8 v[66:69], v[146:149], v[186:189], v[66:69]
	v_mfma_i32_16x16x64_i8 v[18:21], v[154:157], v[186:189], v[18:21]
	v_mfma_i32_16x16x64_i8 v[102:105], v[150:153], v[166:169], v[102:105]
	v_mfma_i32_16x16x64_i8 v[98:101], v[158:161], v[166:169], v[98:101]
	v_mfma_i32_16x16x64_i8 v[94:97], v[150:153], v[174:177], v[94:97]
	v_mfma_i32_16x16x64_i8 v[90:93], v[158:161], v[174:177], v[90:93]
	v_mfma_i32_16x16x64_i8 v[70:73], v[150:153], v[182:185], v[70:73]
	v_mfma_i32_16x16x64_i8 v[22:25], v[158:161], v[182:185], v[22:25]
	v_mfma_i32_16x16x64_i8 v[66:69], v[150:153], v[190:193], v[66:69]
	v_mfma_i32_16x16x64_i8 v[18:21], v[158:161], v[190:193], v[18:21]
	s_barrier
	s_setprio 0
	s_add_i32 s2, s93, s65
	v_lshl_add_u64 v[194:195], v[194:195], 0, s[36:37]
	s_mov_b32 m0, s2
	ds_read_b128 v[162:165], v240 offset:49152
	ds_read_b128 v[166:169], v240 offset:50176
	ds_read_b128 v[170:173], v240 offset:51200
	ds_read_b128 v[174:177], v240 offset:52224
	ds_read_b128 v[178:181], v240 offset:53248
	ds_read_b128 v[182:185], v240 offset:54272
	ds_read_b128 v[186:189], v240 offset:55296
	ds_read_b128 v[190:193], v240 offset:56320
	global_load_lds_dwordx4 v[194:195], off
	s_add_i32 m0, s2, 0x2000
	s_add_u32 s2, s58, 0x80080
	v_lshl_add_u64 v[194:195], v[196:197], 0, s[36:37]
	s_addc_u32 s3, s59, 0
	s_add_i32 s58, s94, s65
	global_load_lds_dwordx4 v[194:195], off
	v_lshl_add_u64 v[194:195], s[2:3], 0, v[206:207]
	s_mov_b32 m0, s58
	s_nop 0
	global_load_lds_dwordx4 v[194:195], off
	v_lshl_add_u64 v[194:195], s[2:3], 0, v[202:203]
	s_add_i32 m0, s58, 0x2000
	s_nop 0
	global_load_lds_dwordx4 v[194:195], off
	v_lshl_add_u64 v[194:195], v[198:199], 0, s[36:37]
	s_mov_b32 m0, s78
	s_nop 0
	global_load_lds_dwordx4 v[194:195], off
	v_lshl_add_u64 v[194:195], v[200:201], 0, s[36:37]
	s_mov_b32 m0, s79
	s_nop 0
	global_load_lds_dwordx4 v[194:195], off
	s_setprio 1
	s_waitcnt vmcnt(8) lgkmcnt(0)
	s_barrier
	v_mfma_i32_16x16x64_i8 v[62:65], v[130:133], v[162:165], v[62:65]
	v_mfma_i32_16x16x64_i8 v[14:17], v[138:141], v[162:165], v[14:17]
	v_mfma_i32_16x16x64_i8 v[58:61], v[130:133], v[170:173], v[58:61]
	v_mfma_i32_16x16x64_i8 v[10:13], v[138:141], v[170:173], v[10:13]
	v_mfma_i32_16x16x64_i8 v[114:117], v[130:133], v[178:181], v[114:117]
	v_mfma_i32_16x16x64_i8 v[106:109], v[138:141], v[178:181], v[106:109]
	v_mfma_i32_16x16x64_i8 v[86:89], v[130:133], v[186:189], v[86:89]
	v_mfma_i32_16x16x64_i8 v[82:85], v[138:141], v[186:189], v[82:85]
	v_mfma_i32_16x16x64_i8 v[62:65], v[134:137], v[166:169], v[62:65]
	v_mfma_i32_16x16x64_i8 v[14:17], v[142:145], v[166:169], v[14:17]
	v_mfma_i32_16x16x64_i8 v[58:61], v[134:137], v[174:177], v[58:61]
	v_mfma_i32_16x16x64_i8 v[10:13], v[142:145], v[174:177], v[10:13]
	v_mfma_i32_16x16x64_i8 v[114:117], v[134:137], v[182:185], v[114:117]
	v_mfma_i32_16x16x64_i8 v[106:109], v[142:145], v[182:185], v[106:109]
	v_mfma_i32_16x16x64_i8 v[86:89], v[134:137], v[190:193], v[86:89]
	v_mfma_i32_16x16x64_i8 v[82:85], v[142:145], v[190:193], v[82:85]
	v_mfma_i32_16x16x64_i8 v[50:53], v[146:149], v[162:165], v[50:53]
	v_mfma_i32_16x16x64_i8 v[6:9], v[154:157], v[162:165], v[6:9]
	v_mfma_i32_16x16x64_i8 v[42:45], v[146:149], v[170:173], v[42:45]
	v_mfma_i32_16x16x64_i8 v[2:5], v[154:157], v[170:173], v[2:5]
	v_mfma_i32_16x16x64_i8 v[54:57], v[146:149], v[178:181], v[54:57]
	v_mfma_i32_16x16x64_i8 v[46:49], v[154:157], v[178:181], v[46:49]
	v_mfma_i32_16x16x64_i8 v[38:41], v[146:149], v[186:189], v[38:41]
	v_mfma_i32_16x16x64_i8 v[34:37], v[154:157], v[186:189], v[34:37]
	v_mfma_i32_16x16x64_i8 v[50:53], v[150:153], v[166:169], v[50:53]
	v_mfma_i32_16x16x64_i8 v[6:9], v[158:161], v[166:169], v[6:9]
	v_mfma_i32_16x16x64_i8 v[42:45], v[150:153], v[174:177], v[42:45]
	v_mfma_i32_16x16x64_i8 v[2:5], v[158:161], v[174:177], v[2:5]
	v_mfma_i32_16x16x64_i8 v[54:57], v[150:153], v[182:185], v[54:57]
	v_mfma_i32_16x16x64_i8 v[46:49], v[158:161], v[182:185], v[46:49]
	v_mfma_i32_16x16x64_i8 v[38:41], v[150:153], v[190:193], v[38:41]
	v_mfma_i32_16x16x64_i8 v[34:37], v[158:161], v[190:193], v[34:37]
	s_barrier
	s_setprio 0
	s_add_i32 s92, s92, 2
	s_add_u32 s90, s90, 0x100
	s_addc_u32 s91, s91, 0
	s_cmp_gt_u32 s92, 29
	s_mov_b64 s[2:3], s[56:57]
	s_cbranch_scc0 .LBB0_845
	s_and_b64 vcc, exec, s[38:39]
	s_cbranch_vccz .LBB0_848
	s_barrier

.LBB0_1099:
	ds_read_b128 v[130:133], v167
	ds_read_b128 v[134:137], v167 offset:1024
	ds_read_b128 v[138:141], v167 offset:2048
	ds_read_b128 v[142:145], v167 offset:3072
	ds_read_b128 v[170:173], v168
	ds_read_b128 v[174:177], v168 offset:1024
	ds_read_b128 v[178:181], v168 offset:2048
	ds_read_b128 v[182:185], v168 offset:3072
	s_add_u32 s30, s28, 0x100
	s_addc_u32 s31, s29, 0
	s_cmpk_eq_i32 s72, 0x52
	s_cselect_b32 s37, s3, s31
	s_cselect_b32 s36, s2, s30
	s_cselect_b32 s35, s27, s71
	s_cselect_b32 s34, s26, s70
	v_lshl_add_u64 v[162:163], s[28:29], 0, v[154:155]
	s_add_i32 m0, s47, 0xc000
	ds_read_b128 v[186:189], v169
	ds_read_b128 v[190:193], v169 offset:1024
	ds_read_b128 v[194:197], v169 offset:2048
	ds_read_b128 v[198:201], v169 offset:3072
	ds_read_b128 v[202:205], v169 offset:4096
	ds_read_b128 v[206:209], v169 offset:5120
	ds_read_b128 v[210:213], v169 offset:6144
	ds_read_b128 v[214:217], v169 offset:7168
	global_load_lds_dwordx4 v[162:163], off
	v_lshl_add_u64 v[162:163], s[28:29], 0, v[156:157]
	s_add_i32 m0, s47, 0xe000
	s_nop 0
	global_load_lds_dwordx4 v[162:163], off
	s_setprio 1
	s_waitcnt vmcnt(8) lgkmcnt(0)
	s_barrier
	v_mfma_i32_16x16x64_i8 v[126:129], v[130:133], v[186:189], v[126:129]
	v_mfma_i32_16x16x64_i8 v[122:125], v[138:141], v[186:189], v[122:125]
	v_mfma_i32_16x16x64_i8 v[110:113], v[130:133], v[194:197], v[110:113]
	v_mfma_i32_16x16x64_i8 v[106:109], v[138:141], v[194:197], v[106:109]
	v_mfma_i32_16x16x64_i8 v[94:97], v[130:133], v[202:205], v[94:97]
	v_mfma_i32_16x16x64_i8 v[90:93], v[138:141], v[202:205], v[90:93]
	v_mfma_i32_16x16x64_i8 v[78:81], v[130:133], v[210:213], v[78:81]
	v_mfma_i32_16x16x64_i8 v[74:77], v[138:141], v[210:213], v[74:77]
	v_mfma_i32_16x16x64_i8 v[126:129], v[134:137], v[190:193], v[126:129]
	v_mfma_i32_16x16x64_i8 v[122:125], v[142:145], v[190:193], v[122:125]
	v_mfma_i32_16x16x64_i8 v[110:113], v[134:137], v[198:201], v[110:113]
	v_mfma_i32_16x16x64_i8 v[106:109], v[142:145], v[198:201], v[106:109]
	v_mfma_i32_16x16x64_i8 v[94:97], v[134:137], v[206:209], v[94:97]
	v_mfma_i32_16x16x64_i8 v[90:93], v[142:145], v[206:209], v[90:93]
	v_mfma_i32_16x16x64_i8 v[78:81], v[134:137], v[214:217], v[78:81]
	v_mfma_i32_16x16x64_i8 v[74:77], v[142:145], v[214:217], v[74:77]
	v_mfma_i32_16x16x64_i8 v[118:121], v[170:173], v[186:189], v[118:121]
	v_mfma_i32_16x16x64_i8 v[114:117], v[178:181], v[186:189], v[114:117]
	v_mfma_i32_16x16x64_i8 v[102:105], v[170:173], v[194:197], v[102:105]
	v_mfma_i32_16x16x64_i8 v[98:101], v[178:181], v[194:197], v[98:101]
	v_mfma_i32_16x16x64_i8 v[86:89], v[170:173], v[202:205], v[86:89]
	v_mfma_i32_16x16x64_i8 v[82:85], v[178:181], v[202:205], v[82:85]
	v_mfma_i32_16x16x64_i8 v[70:73], v[170:173], v[210:213], v[70:73]
	v_mfma_i32_16x16x64_i8 v[66:69], v[178:181], v[210:213], v[66:69]
	v_mfma_i32_16x16x64_i8 v[118:121], v[174:177], v[190:193], v[118:121]
	v_mfma_i32_16x16x64_i8 v[114:117], v[182:185], v[190:193], v[114:117]
	v_mfma_i32_16x16x64_i8 v[102:105], v[174:177], v[198:201], v[102:105]
	v_mfma_i32_16x16x64_i8 v[98:101], v[182:185], v[198:201], v[98:101]
	v_mfma_i32_16x16x64_i8 v[86:89], v[174:177], v[206:209], v[86:89]
	v_mfma_i32_16x16x64_i8 v[82:85], v[182:185], v[206:209], v[82:85]
	v_mfma_i32_16x16x64_i8 v[70:73], v[174:177], v[214:217], v[70:73]
	v_mfma_i32_16x16x64_i8 v[66:69], v[182:185], v[214:217], v[66:69]
	s_barrier
	s_setprio 0
	s_add_i32 s28, s56, s46
	v_lshl_add_u64 v[162:163], s[34:35], 0, v[150:151]
	s_mov_b32 m0, s28
	ds_read_b128 v[186:189], v169 offset:16384
	ds_read_b128 v[190:193], v169 offset:17408
	ds_read_b128 v[194:197], v169 offset:18432
	ds_read_b128 v[198:201], v169 offset:19456
	ds_read_b128 v[202:205], v169 offset:20480
	ds_read_b128 v[206:209], v169 offset:21504
	ds_read_b128 v[210:213], v169 offset:22528
	ds_read_b128 v[214:217], v169 offset:23552
	global_load_lds_dwordx4 v[162:163], off
	s_add_i32 m0, s28, 0x2000
	s_add_u32 s28, s34, 0x158000
	v_lshl_add_u64 v[218:219], s[34:35], 0, v[146:147]
	s_addc_u32 s29, s35, 0
	s_add_i32 s73, s57, s46
	global_load_lds_dwordx4 v[218:219], off
	v_lshl_add_u64 v[220:221], s[28:29], 0, v[150:151]
	s_mov_b32 m0, s73
	v_lshl_add_u64 v[222:223], s[36:37], 0, v[148:149]
	global_load_lds_dwordx4 v[220:221], off
	v_lshl_add_u64 v[220:221], s[28:29], 0, v[146:147]
	s_add_i32 m0, s73, 0x2000
	s_nop 0
	global_load_lds_dwordx4 v[220:221], off
	v_lshl_add_u64 v[220:221], s[36:37], 0, v[152:153]
	s_mov_b32 m0, s47
	s_nop 0
	global_load_lds_dwordx4 v[220:221], off
	s_mov_b32 m0, s48
	s_nop 0
	global_load_lds_dwordx4 v[222:223], off
	s_setprio 1
	s_waitcnt vmcnt(8) lgkmcnt(0)
	s_barrier
	v_mfma_i32_16x16x64_i8 v[62:65], v[130:133], v[186:189], v[62:65]
	v_mfma_i32_16x16x64_i8 v[58:61], v[138:141], v[186:189], v[58:61]
	v_mfma_i32_16x16x64_i8 v[46:49], v[130:133], v[194:197], v[46:49]
	v_mfma_i32_16x16x64_i8 v[42:45], v[138:141], v[194:197], v[42:45]
	v_mfma_i32_16x16x64_i8 v[30:33], v[130:133], v[202:205], v[30:33]
	v_mfma_i32_16x16x64_i8 v[26:29], v[138:141], v[202:205], v[26:29]
	v_mfma_i32_16x16x64_i8 v[14:17], v[130:133], v[210:213], v[14:17]
	v_mfma_i32_16x16x64_i8 v[10:13], v[138:141], v[210:213], v[10:13]
	v_mfma_i32_16x16x64_i8 v[62:65], v[134:137], v[190:193], v[62:65]
	v_mfma_i32_16x16x64_i8 v[58:61], v[142:145], v[190:193], v[58:61]
	v_mfma_i32_16x16x64_i8 v[46:49], v[134:137], v[198:201], v[46:49]
	v_mfma_i32_16x16x64_i8 v[42:45], v[142:145], v[198:201], v[42:45]
	v_mfma_i32_16x16x64_i8 v[30:33], v[134:137], v[206:209], v[30:33]
	v_mfma_i32_16x16x64_i8 v[26:29], v[142:145], v[206:209], v[26:29]
	v_mfma_i32_16x16x64_i8 v[14:17], v[134:137], v[214:217], v[14:17]
	v_mfma_i32_16x16x64_i8 v[10:13], v[142:145], v[214:217], v[10:13]
	v_mfma_i32_16x16x64_i8 v[54:57], v[170:173], v[186:189], v[54:57]
	v_mfma_i32_16x16x64_i8 v[50:53], v[178:181], v[186:189], v[50:53]
	v_mfma_i32_16x16x64_i8 v[38:41], v[170:173], v[194:197], v[38:41]
	v_mfma_i32_16x16x64_i8 v[34:37], v[178:181], v[194:197], v[34:37]
	v_mfma_i32_16x16x64_i8 v[22:25], v[170:173], v[202:205], v[22:25]
	v_mfma_i32_16x16x64_i8 v[18:21], v[178:181], v[202:205], v[18:21]
	v_mfma_i32_16x16x64_i8 v[6:9], v[170:173], v[210:213], v[6:9]
	v_mfma_i32_16x16x64_i8 v[2:5], v[178:181], v[210:213], v[2:5]
	v_mfma_i32_16x16x64_i8 v[54:57], v[174:177], v[190:193], v[54:57]
	v_mfma_i32_16x16x64_i8 v[50:53], v[182:185], v[190:193], v[50:53]
	v_mfma_i32_16x16x64_i8 v[38:41], v[174:177], v[198:201], v[38:41]
	v_mfma_i32_16x16x64_i8 v[34:37], v[182:185], v[198:201], v[34:37]
	v_mfma_i32_16x16x64_i8 v[22:25], v[174:177], v[206:209], v[22:25]
	v_mfma_i32_16x16x64_i8 v[18:21], v[182:185], v[206:209], v[18:21]
	v_mfma_i32_16x16x64_i8 v[6:9], v[174:177], v[214:217], v[6:9]
	v_mfma_i32_16x16x64_i8 v[2:5], v[182:185], v[214:217], v[2:5]
	s_barrier
	s_setprio 0
	s_add_i32 s73, 0, 0x18000
	s_add_i32 s74, 0, 0x1c000
	v_add_u32_e32 v142, s73, v166
	v_add_u32_e32 v182, s74, v166
	ds_read_b128 v[130:133], v142
	ds_read_b128 v[134:137], v142 offset:1024
	ds_read_b128 v[138:141], v142 offset:2048
	ds_read_b128 v[142:145], v142 offset:3072
	ds_read_b128 v[170:173], v182
	ds_read_b128 v[174:177], v182 offset:1024
	ds_read_b128 v[178:181], v182 offset:2048
	ds_read_b128 v[182:185], v182 offset:3072
	s_add_u32 s28, s36, 0x158000
	s_addc_u32 s29, s37, 0
	s_mov_b32 m0, s49
	v_lshl_add_u64 v[224:225], s[28:29], 0, v[152:153]
	ds_read_b128 v[186:189], v169 offset:32768
	ds_read_b128 v[190:193], v169 offset:33792
	ds_read_b128 v[194:197], v169 offset:34816
	ds_read_b128 v[198:201], v169 offset:35840
	ds_read_b128 v[202:205], v169 offset:36864
	ds_read_b128 v[206:209], v169 offset:37888
	ds_read_b128 v[210:213], v169 offset:38912
	ds_read_b128 v[214:217], v169 offset:39936
	global_load_lds_dwordx4 v[224:225], off
	v_lshl_add_u64 v[224:225], s[28:29], 0, v[148:149]
	s_mov_b32 m0, s50
	s_nop 0
	global_load_lds_dwordx4 v[224:225], off
	s_setprio 1
	s_waitcnt vmcnt(8) lgkmcnt(0)
	s_barrier
	v_mfma_i32_16x16x64_i8 v[126:129], v[130:133], v[186:189], v[126:129]
	v_mfma_i32_16x16x64_i8 v[122:125], v[138:141], v[186:189], v[122:125]
	v_mfma_i32_16x16x64_i8 v[110:113], v[130:133], v[194:197], v[110:113]
	v_mfma_i32_16x16x64_i8 v[106:109], v[138:141], v[194:197], v[106:109]
	v_mfma_i32_16x16x64_i8 v[94:97], v[130:133], v[202:205], v[94:97]
	v_mfma_i32_16x16x64_i8 v[90:93], v[138:141], v[202:205], v[90:93]
	v_mfma_i32_16x16x64_i8 v[78:81], v[130:133], v[210:213], v[78:81]
	v_mfma_i32_16x16x64_i8 v[74:77], v[138:141], v[210:213], v[74:77]
	v_mfma_i32_16x16x64_i8 v[126:129], v[134:137], v[190:193], v[126:129]
	v_mfma_i32_16x16x64_i8 v[122:125], v[142:145], v[190:193], v[122:125]
	v_mfma_i32_16x16x64_i8 v[110:113], v[134:137], v[198:201], v[110:113]
	v_mfma_i32_16x16x64_i8 v[106:109], v[142:145], v[198:201], v[106:109]
	v_mfma_i32_16x16x64_i8 v[94:97], v[134:137], v[206:209], v[94:97]
	v_mfma_i32_16x16x64_i8 v[90:93], v[142:145], v[206:209], v[90:93]
	v_mfma_i32_16x16x64_i8 v[78:81], v[134:137], v[214:217], v[78:81]
	v_mfma_i32_16x16x64_i8 v[74:77], v[142:145], v[214:217], v[74:77]
	v_mfma_i32_16x16x64_i8 v[118:121], v[170:173], v[186:189], v[118:121]
	v_mfma_i32_16x16x64_i8 v[114:117], v[178:181], v[186:189], v[114:117]
	v_mfma_i32_16x16x64_i8 v[102:105], v[170:173], v[194:197], v[102:105]
	v_mfma_i32_16x16x64_i8 v[98:101], v[178:181], v[194:197], v[98:101]
	v_mfma_i32_16x16x64_i8 v[86:89], v[170:173], v[202:205], v[86:89]
	v_mfma_i32_16x16x64_i8 v[82:85], v[178:181], v[202:205], v[82:85]
	v_mfma_i32_16x16x64_i8 v[70:73], v[170:173], v[210:213], v[70:73]
	v_mfma_i32_16x16x64_i8 v[66:69], v[178:181], v[210:213], v[66:69]
	v_mfma_i32_16x16x64_i8 v[118:121], v[174:177], v[190:193], v[118:121]
	v_mfma_i32_16x16x64_i8 v[114:117], v[182:185], v[190:193], v[114:117]
	v_mfma_i32_16x16x64_i8 v[102:105], v[174:177], v[198:201], v[102:105]
	v_mfma_i32_16x16x64_i8 v[98:101], v[182:185], v[198:201], v[98:101]
	v_mfma_i32_16x16x64_i8 v[86:89], v[174:177], v[206:209], v[86:89]
	v_mfma_i32_16x16x64_i8 v[82:85], v[182:185], v[206:209], v[82:85]
	v_mfma_i32_16x16x64_i8 v[70:73], v[174:177], v[214:217], v[70:73]
	v_mfma_i32_16x16x64_i8 v[66:69], v[182:185], v[214:217], v[66:69]
	s_barrier
	s_setprio 0
	s_add_i32 s28, s73, s46
	v_lshl_add_u64 v[162:163], v[162:163], 0, s[14:15]
	s_mov_b32 m0, s28
	ds_read_b128 v[186:189], v169 offset:49152
	ds_read_b128 v[190:193], v169 offset:50176
	ds_read_b128 v[194:197], v169 offset:51200
	ds_read_b128 v[198:201], v169 offset:52224
	ds_read_b128 v[202:205], v169 offset:53248
	ds_read_b128 v[206:209], v169 offset:54272
	ds_read_b128 v[210:213], v169 offset:55296
	ds_read_b128 v[214:217], v169 offset:56320
	global_load_lds_dwordx4 v[162:163], off
	s_add_i32 m0, s28, 0x2000
	s_add_u32 s28, s34, 0x158080
	v_lshl_add_u64 v[162:163], v[218:219], 0, s[14:15]
	s_addc_u32 s29, s35, 0
	s_add_i32 s34, s74, s46
	global_load_lds_dwordx4 v[162:163], off
	v_lshl_add_u64 v[162:163], s[28:29], 0, v[150:151]
	s_mov_b32 m0, s34
	s_nop 0
	global_load_lds_dwordx4 v[162:163], off
	v_lshl_add_u64 v[162:163], s[28:29], 0, v[146:147]
	s_add_i32 m0, s34, 0x2000
	s_nop 0
	global_load_lds_dwordx4 v[162:163], off
	v_lshl_add_u64 v[162:163], v[220:221], 0, s[14:15]
	s_mov_b32 m0, s54
	s_nop 0
	global_load_lds_dwordx4 v[162:163], off
	v_lshl_add_u64 v[162:163], v[222:223], 0, s[14:15]
	s_mov_b32 m0, s55
	s_nop 0
	global_load_lds_dwordx4 v[162:163], off
	s_setprio 1
	s_waitcnt vmcnt(8) lgkmcnt(0)
	s_barrier
	v_mfma_i32_16x16x64_i8 v[62:65], v[130:133], v[186:189], v[62:65]
	v_mfma_i32_16x16x64_i8 v[58:61], v[138:141], v[186:189], v[58:61]
	v_mfma_i32_16x16x64_i8 v[46:49], v[130:133], v[194:197], v[46:49]
	v_mfma_i32_16x16x64_i8 v[42:45], v[138:141], v[194:197], v[42:45]
	v_mfma_i32_16x16x64_i8 v[30:33], v[130:133], v[202:205], v[30:33]
	v_mfma_i32_16x16x64_i8 v[26:29], v[138:141], v[202:205], v[26:29]
	v_mfma_i32_16x16x64_i8 v[14:17], v[130:133], v[210:213], v[14:17]
	v_mfma_i32_16x16x64_i8 v[10:13], v[138:141], v[210:213], v[10:13]
	v_mfma_i32_16x16x64_i8 v[62:65], v[134:137], v[190:193], v[62:65]
	v_mfma_i32_16x16x64_i8 v[58:61], v[142:145], v[190:193], v[58:61]
	v_mfma_i32_16x16x64_i8 v[46:49], v[134:137], v[198:201], v[46:49]
	v_mfma_i32_16x16x64_i8 v[42:45], v[142:145], v[198:201], v[42:45]
	v_mfma_i32_16x16x64_i8 v[30:33], v[134:137], v[206:209], v[30:33]
	v_mfma_i32_16x16x64_i8 v[26:29], v[142:145], v[206:209], v[26:29]
	v_mfma_i32_16x16x64_i8 v[14:17], v[134:137], v[214:217], v[14:17]
	v_mfma_i32_16x16x64_i8 v[10:13], v[142:145], v[214:217], v[10:13]
	v_mfma_i32_16x16x64_i8 v[54:57], v[170:173], v[186:189], v[54:57]
	v_mfma_i32_16x16x64_i8 v[50:53], v[178:181], v[186:189], v[50:53]
	v_mfma_i32_16x16x64_i8 v[38:41], v[170:173], v[194:197], v[38:41]
	v_mfma_i32_16x16x64_i8 v[34:37], v[178:181], v[194:197], v[34:37]
	v_mfma_i32_16x16x64_i8 v[22:25], v[170:173], v[202:205], v[22:25]
	v_mfma_i32_16x16x64_i8 v[18:21], v[178:181], v[202:205], v[18:21]
	v_mfma_i32_16x16x64_i8 v[6:9], v[170:173], v[210:213], v[6:9]
	v_mfma_i32_16x16x64_i8 v[2:5], v[178:181], v[210:213], v[2:5]
	v_mfma_i32_16x16x64_i8 v[54:57], v[174:177], v[190:193], v[54:57]
	v_mfma_i32_16x16x64_i8 v[50:53], v[182:185], v[190:193], v[50:53]
	v_mfma_i32_16x16x64_i8 v[38:41], v[174:177], v[198:201], v[38:41]
	v_mfma_i32_16x16x64_i8 v[34:37], v[182:185], v[198:201], v[34:37]
	v_mfma_i32_16x16x64_i8 v[22:25], v[174:177], v[206:209], v[22:25]
	v_mfma_i32_16x16x64_i8 v[18:21], v[182:185], v[206:209], v[18:21]
	v_mfma_i32_16x16x64_i8 v[6:9], v[174:177], v[214:217], v[6:9]
	v_mfma_i32_16x16x64_i8 v[2:5], v[182:185], v[214:217], v[2:5]
	s_barrier
	s_setprio 0
	s_add_i32 s72, s72, 2
	s_add_u32 s70, s70, 0x100
	s_addc_u32 s71, s71, 0
	s_cmpk_gt_u32 s72, 0x53
	s_mov_b64 s[28:29], s[30:31]
	s_cbranch_scc0 .LBB0_1099
	s_and_b64 vcc, exec, s[16:17]
	s_cbranch_vccz .LBB0_1102
	s_barrier

.LBB0_1246:
	ds_read_b128 v[130:133], v193
	ds_read_b128 v[134:137], v193 offset:1024
	ds_read_b128 v[138:141], v193 offset:2048
	ds_read_b128 v[142:145], v193 offset:3072
	ds_read_b128 v[162:165], v194
	ds_read_b128 v[166:169], v194 offset:1024
	ds_read_b128 v[170:173], v194 offset:2048
	ds_read_b128 v[174:177], v194 offset:3072
	s_add_u32 s30, s28, 0xfff00080
	s_addc_u32 s31, s29, -1
	s_cmp_eq_u32 s68, 60
	s_cselect_b32 s35, s3, s31
	s_cselect_b32 s34, s23, s30
	s_cselect_b32 s31, s17, s65
	s_cselect_b32 s30, s62, s63
	v_lshl_add_u64 v[216:217], s[28:29], 0, v[154:155]
	s_add_i32 m0, s45, 0xc000
	ds_read_b128 v[178:181], v195
	ds_read_b128 v[182:185], v195 offset:1024
	ds_read_b128 v[186:189], v195 offset:2048
	ds_read_b128 v[196:199], v195 offset:3072
	ds_read_b128 v[200:203], v195 offset:4096
	ds_read_b128 v[204:207], v195 offset:5120
	ds_read_b128 v[208:211], v195 offset:6144
	ds_read_b128 v[212:215], v195 offset:7168
	global_load_lds_dwordx4 v[216:217], off
	v_lshl_add_u64 v[216:217], s[28:29], 0, v[156:157]
	s_add_i32 m0, s45, 0xe000
	s_nop 0
	global_load_lds_dwordx4 v[216:217], off
	s_setprio 1
	s_waitcnt vmcnt(8) lgkmcnt(0)
	s_barrier
	v_mfma_f32_16x16x32_bf16 v[126:129], v[130:133], v[178:181], v[126:129]
	v_mfma_f32_16x16x32_bf16 v[122:125], v[138:141], v[178:181], v[122:125]
	v_mfma_f32_16x16x32_bf16 v[118:121], v[130:133], v[186:189], v[118:121]
	v_mfma_f32_16x16x32_bf16 v[110:113], v[138:141], v[186:189], v[110:113]
	v_mfma_f32_16x16x32_bf16 v[98:101], v[130:133], v[200:203], v[98:101]
	v_mfma_f32_16x16x32_bf16 v[90:93], v[138:141], v[200:203], v[90:93]
	v_mfma_f32_16x16x32_bf16 v[82:85], v[130:133], v[208:211], v[82:85]
	v_mfma_f32_16x16x32_bf16 v[74:77], v[138:141], v[208:211], v[74:77]
	v_mfma_f32_16x16x32_bf16 v[126:129], v[134:137], v[182:185], v[126:129]
	v_mfma_f32_16x16x32_bf16 v[122:125], v[142:145], v[182:185], v[122:125]
	v_mfma_f32_16x16x32_bf16 v[118:121], v[134:137], v[196:199], v[118:121]
	v_mfma_f32_16x16x32_bf16 v[110:113], v[142:145], v[196:199], v[110:113]
	v_mfma_f32_16x16x32_bf16 v[98:101], v[134:137], v[204:207], v[98:101]
	v_mfma_f32_16x16x32_bf16 v[90:93], v[142:145], v[204:207], v[90:93]
	v_mfma_f32_16x16x32_bf16 v[82:85], v[134:137], v[212:215], v[82:85]
	v_mfma_f32_16x16x32_bf16 v[74:77], v[142:145], v[212:215], v[74:77]
	v_mfma_f32_16x16x32_bf16 v[114:117], v[162:165], v[178:181], v[114:117]
	v_mfma_f32_16x16x32_bf16 v[106:109], v[170:173], v[178:181], v[106:109]
	v_mfma_f32_16x16x32_bf16 v[102:105], v[162:165], v[186:189], v[102:105]
	v_mfma_f32_16x16x32_bf16 v[94:97], v[170:173], v[186:189], v[94:97]
	v_mfma_f32_16x16x32_bf16 v[86:89], v[162:165], v[200:203], v[86:89]
	v_mfma_f32_16x16x32_bf16 v[78:81], v[170:173], v[200:203], v[78:81]
	v_mfma_f32_16x16x32_bf16 v[70:73], v[162:165], v[208:211], v[70:73]
	v_mfma_f32_16x16x32_bf16 v[66:69], v[170:173], v[208:211], v[66:69]
	v_mfma_f32_16x16x32_bf16 v[114:117], v[166:169], v[182:185], v[114:117]
	v_mfma_f32_16x16x32_bf16 v[106:109], v[174:177], v[182:185], v[106:109]
	v_mfma_f32_16x16x32_bf16 v[102:105], v[166:169], v[196:199], v[102:105]
	v_mfma_f32_16x16x32_bf16 v[94:97], v[174:177], v[196:199], v[94:97]
	v_mfma_f32_16x16x32_bf16 v[86:89], v[166:169], v[204:207], v[86:89]
	v_mfma_f32_16x16x32_bf16 v[78:81], v[174:177], v[204:207], v[78:81]
	v_mfma_f32_16x16x32_bf16 v[70:73], v[166:169], v[212:215], v[70:73]
	v_mfma_f32_16x16x32_bf16 v[66:69], v[174:177], v[212:215], v[66:69]
	s_barrier
	s_setprio 0
	s_add_i32 s69, s58, s44
	v_lshl_add_u64 v[216:217], s[30:31], 0, v[148:149]
	s_mov_b32 m0, s69
	ds_read_b128 v[178:181], v195 offset:16384
	ds_read_b128 v[182:185], v195 offset:17408
	ds_read_b128 v[186:189], v195 offset:18432
	ds_read_b128 v[196:199], v195 offset:19456
	ds_read_b128 v[200:203], v195 offset:20480
	ds_read_b128 v[204:207], v195 offset:21504
	ds_read_b128 v[208:211], v195 offset:22528
	ds_read_b128 v[212:215], v195 offset:23552
	global_load_lds_dwordx4 v[216:217], off
	s_add_i32 m0, s69, 0x2000
	s_add_u32 s70, s30, 0x100000
	v_lshl_add_u64 v[218:219], s[30:31], 0, v[152:153]
	s_addc_u32 s71, s31, 0
	s_add_i32 s69, s59, s44
	global_load_lds_dwordx4 v[218:219], off
	v_lshl_add_u64 v[220:221], s[70:71], 0, v[148:149]
	s_mov_b32 m0, s69
	v_lshl_add_u64 v[222:223], s[34:35], 0, v[150:151]
	global_load_lds_dwordx4 v[220:221], off
	v_lshl_add_u64 v[220:221], s[70:71], 0, v[152:153]
	s_add_i32 m0, s69, 0x2000
	s_nop 0
	global_load_lds_dwordx4 v[220:221], off
	v_lshl_add_u64 v[220:221], s[34:35], 0, v[146:147]
	s_mov_b32 m0, s45
	s_nop 0
	global_load_lds_dwordx4 v[220:221], off
	s_mov_b32 m0, s46
	s_nop 0
	global_load_lds_dwordx4 v[222:223], off
	s_setprio 1
	s_waitcnt vmcnt(8) lgkmcnt(0)
	s_barrier
	v_mfma_f32_16x16x32_bf16 v[62:65], v[130:133], v[178:181], v[62:65]
	v_mfma_f32_16x16x32_bf16 v[58:61], v[138:141], v[178:181], v[58:61]
	v_mfma_f32_16x16x32_bf16 v[46:49], v[130:133], v[186:189], v[46:49]
	v_mfma_f32_16x16x32_bf16 v[42:45], v[138:141], v[186:189], v[42:45]
	v_mfma_f32_16x16x32_bf16 v[30:33], v[130:133], v[200:203], v[30:33]
	v_mfma_f32_16x16x32_bf16 v[26:29], v[138:141], v[200:203], v[26:29]
	v_mfma_f32_16x16x32_bf16 v[14:17], v[130:133], v[208:211], v[14:17]
	v_mfma_f32_16x16x32_bf16 v[10:13], v[138:141], v[208:211], v[10:13]
	v_mfma_f32_16x16x32_bf16 v[62:65], v[134:137], v[182:185], v[62:65]
	v_mfma_f32_16x16x32_bf16 v[58:61], v[142:145], v[182:185], v[58:61]
	v_mfma_f32_16x16x32_bf16 v[46:49], v[134:137], v[196:199], v[46:49]
	v_mfma_f32_16x16x32_bf16 v[42:45], v[142:145], v[196:199], v[42:45]
	v_mfma_f32_16x16x32_bf16 v[30:33], v[134:137], v[204:207], v[30:33]
	v_mfma_f32_16x16x32_bf16 v[26:29], v[142:145], v[204:207], v[26:29]
	v_mfma_f32_16x16x32_bf16 v[14:17], v[134:137], v[212:215], v[14:17]
	v_mfma_f32_16x16x32_bf16 v[10:13], v[142:145], v[212:215], v[10:13]
	v_mfma_f32_16x16x32_bf16 v[54:57], v[162:165], v[178:181], v[54:57]
	v_mfma_f32_16x16x32_bf16 v[50:53], v[170:173], v[178:181], v[50:53]
	v_mfma_f32_16x16x32_bf16 v[38:41], v[162:165], v[186:189], v[38:41]
	v_mfma_f32_16x16x32_bf16 v[34:37], v[170:173], v[186:189], v[34:37]
	v_mfma_f32_16x16x32_bf16 v[22:25], v[162:165], v[200:203], v[22:25]
	v_mfma_f32_16x16x32_bf16 v[18:21], v[170:173], v[200:203], v[18:21]
	v_mfma_f32_16x16x32_bf16 v[6:9], v[162:165], v[208:211], v[6:9]
	v_mfma_f32_16x16x32_bf16 v[2:5], v[170:173], v[208:211], v[2:5]
	v_mfma_f32_16x16x32_bf16 v[54:57], v[166:169], v[182:185], v[54:57]
	v_mfma_f32_16x16x32_bf16 v[50:53], v[174:177], v[182:185], v[50:53]
	v_mfma_f32_16x16x32_bf16 v[38:41], v[166:169], v[196:199], v[38:41]
	v_mfma_f32_16x16x32_bf16 v[34:37], v[174:177], v[196:199], v[34:37]
	v_mfma_f32_16x16x32_bf16 v[22:25], v[166:169], v[204:207], v[22:25]
	v_mfma_f32_16x16x32_bf16 v[18:21], v[174:177], v[204:207], v[18:21]
	v_mfma_f32_16x16x32_bf16 v[6:9], v[166:169], v[212:215], v[6:9]
	v_mfma_f32_16x16x32_bf16 v[2:5], v[174:177], v[212:215], v[2:5]
	s_barrier
	s_setprio 0
	s_add_i32 s69, 0, 0x18000
	s_add_i32 s70, 0, 0x1c000
	v_add_u32_e32 v142, s69, v192
	v_add_u32_e32 v174, s70, v192
	ds_read_b128 v[130:133], v142
	ds_read_b128 v[134:137], v142 offset:1024
	ds_read_b128 v[138:141], v142 offset:2048
	ds_read_b128 v[142:145], v142 offset:3072
	ds_read_b128 v[162:165], v174
	ds_read_b128 v[166:169], v174 offset:1024
	ds_read_b128 v[170:173], v174 offset:2048
	ds_read_b128 v[174:177], v174 offset:3072
	s_add_u32 s34, s34, 0x100000
	s_addc_u32 s35, s35, 0
	s_mov_b32 m0, s47
	v_lshl_add_u64 v[224:225], s[34:35], 0, v[146:147]
	ds_read_b128 v[178:181], v195 offset:32768
	ds_read_b128 v[182:185], v195 offset:33792
	ds_read_b128 v[186:189], v195 offset:34816
	ds_read_b128 v[196:199], v195 offset:35840
	ds_read_b128 v[200:203], v195 offset:36864
	ds_read_b128 v[204:207], v195 offset:37888
	ds_read_b128 v[208:211], v195 offset:38912
	ds_read_b128 v[212:215], v195 offset:39936
	global_load_lds_dwordx4 v[224:225], off
	v_lshl_add_u64 v[224:225], s[34:35], 0, v[150:151]
	s_mov_b32 m0, s48
	s_nop 0
	global_load_lds_dwordx4 v[224:225], off
	s_setprio 1
	s_waitcnt vmcnt(8) lgkmcnt(0)
	s_barrier
	v_mfma_f32_16x16x32_bf16 v[126:129], v[130:133], v[178:181], v[126:129]
	v_mfma_f32_16x16x32_bf16 v[122:125], v[138:141], v[178:181], v[122:125]
	v_mfma_f32_16x16x32_bf16 v[118:121], v[130:133], v[186:189], v[118:121]
	v_mfma_f32_16x16x32_bf16 v[110:113], v[138:141], v[186:189], v[110:113]
	v_mfma_f32_16x16x32_bf16 v[98:101], v[130:133], v[200:203], v[98:101]
	v_mfma_f32_16x16x32_bf16 v[90:93], v[138:141], v[200:203], v[90:93]
	v_mfma_f32_16x16x32_bf16 v[82:85], v[130:133], v[208:211], v[82:85]
	v_mfma_f32_16x16x32_bf16 v[74:77], v[138:141], v[208:211], v[74:77]
	v_mfma_f32_16x16x32_bf16 v[126:129], v[134:137], v[182:185], v[126:129]
	v_mfma_f32_16x16x32_bf16 v[122:125], v[142:145], v[182:185], v[122:125]
	v_mfma_f32_16x16x32_bf16 v[118:121], v[134:137], v[196:199], v[118:121]
	v_mfma_f32_16x16x32_bf16 v[110:113], v[142:145], v[196:199], v[110:113]
	v_mfma_f32_16x16x32_bf16 v[98:101], v[134:137], v[204:207], v[98:101]
	v_mfma_f32_16x16x32_bf16 v[90:93], v[142:145], v[204:207], v[90:93]
	v_mfma_f32_16x16x32_bf16 v[82:85], v[134:137], v[212:215], v[82:85]
	v_mfma_f32_16x16x32_bf16 v[74:77], v[142:145], v[212:215], v[74:77]
	v_mfma_f32_16x16x32_bf16 v[114:117], v[162:165], v[178:181], v[114:117]
	v_mfma_f32_16x16x32_bf16 v[106:109], v[170:173], v[178:181], v[106:109]
	v_mfma_f32_16x16x32_bf16 v[102:105], v[162:165], v[186:189], v[102:105]
	v_mfma_f32_16x16x32_bf16 v[94:97], v[170:173], v[186:189], v[94:97]
	v_mfma_f32_16x16x32_bf16 v[86:89], v[162:165], v[200:203], v[86:89]
	v_mfma_f32_16x16x32_bf16 v[78:81], v[170:173], v[200:203], v[78:81]
	v_mfma_f32_16x16x32_bf16 v[70:73], v[162:165], v[208:211], v[70:73]
	v_mfma_f32_16x16x32_bf16 v[66:69], v[170:173], v[208:211], v[66:69]
	v_mfma_f32_16x16x32_bf16 v[114:117], v[166:169], v[182:185], v[114:117]
	v_mfma_f32_16x16x32_bf16 v[106:109], v[174:177], v[182:185], v[106:109]
	v_mfma_f32_16x16x32_bf16 v[102:105], v[166:169], v[196:199], v[102:105]
	v_mfma_f32_16x16x32_bf16 v[94:97], v[174:177], v[196:199], v[94:97]
	v_mfma_f32_16x16x32_bf16 v[86:89], v[166:169], v[204:207], v[86:89]
	v_mfma_f32_16x16x32_bf16 v[78:81], v[174:177], v[204:207], v[78:81]
	v_mfma_f32_16x16x32_bf16 v[70:73], v[166:169], v[212:215], v[70:73]
	v_mfma_f32_16x16x32_bf16 v[66:69], v[174:177], v[212:215], v[66:69]
	s_barrier
	s_setprio 0
	s_add_i32 s34, s69, s44
	v_lshl_add_u64 v[216:217], v[216:217], 0, s[12:13]
	s_mov_b32 m0, s34
	ds_read_b128 v[178:181], v195 offset:49152
	ds_read_b128 v[182:185], v195 offset:50176
	ds_read_b128 v[186:189], v195 offset:51200
	ds_read_b128 v[196:199], v195 offset:52224
	ds_read_b128 v[200:203], v195 offset:53248
	ds_read_b128 v[204:207], v195 offset:54272
	ds_read_b128 v[208:211], v195 offset:55296
	ds_read_b128 v[212:215], v195 offset:56320
	global_load_lds_dwordx4 v[216:217], off
	s_add_i32 m0, s34, 0x2000
	s_add_u32 s30, s30, 0x100080
	v_lshl_add_u64 v[216:217], v[218:219], 0, s[12:13]
	s_addc_u32 s31, s31, 0
	s_add_i32 s34, s70, s44
	global_load_lds_dwordx4 v[216:217], off
	v_lshl_add_u64 v[216:217], s[30:31], 0, v[148:149]
	s_mov_b32 m0, s34
	s_nop 0
	global_load_lds_dwordx4 v[216:217], off
	v_lshl_add_u64 v[216:217], s[30:31], 0, v[152:153]
	s_add_i32 m0, s34, 0x2000
	s_nop 0
	global_load_lds_dwordx4 v[216:217], off
	v_lshl_add_u64 v[216:217], v[220:221], 0, s[12:13]
	s_mov_b32 m0, s55
	s_nop 0
	global_load_lds_dwordx4 v[216:217], off
	v_lshl_add_u64 v[216:217], v[222:223], 0, s[12:13]
	s_mov_b32 m0, s56
	s_nop 0
	global_load_lds_dwordx4 v[216:217], off
	s_setprio 1
	s_waitcnt vmcnt(8) lgkmcnt(0)
	s_barrier
	v_mfma_f32_16x16x32_bf16 v[62:65], v[130:133], v[178:181], v[62:65]
	v_mfma_f32_16x16x32_bf16 v[58:61], v[138:141], v[178:181], v[58:61]
	v_mfma_f32_16x16x32_bf16 v[46:49], v[130:133], v[186:189], v[46:49]
	v_mfma_f32_16x16x32_bf16 v[42:45], v[138:141], v[186:189], v[42:45]
	v_mfma_f32_16x16x32_bf16 v[30:33], v[130:133], v[200:203], v[30:33]
	v_mfma_f32_16x16x32_bf16 v[26:29], v[138:141], v[200:203], v[26:29]
	v_mfma_f32_16x16x32_bf16 v[14:17], v[130:133], v[208:211], v[14:17]
	v_mfma_f32_16x16x32_bf16 v[10:13], v[138:141], v[208:211], v[10:13]
	v_mfma_f32_16x16x32_bf16 v[62:65], v[134:137], v[182:185], v[62:65]
	v_mfma_f32_16x16x32_bf16 v[58:61], v[142:145], v[182:185], v[58:61]
	v_mfma_f32_16x16x32_bf16 v[46:49], v[134:137], v[196:199], v[46:49]
	v_mfma_f32_16x16x32_bf16 v[42:45], v[142:145], v[196:199], v[42:45]
	v_mfma_f32_16x16x32_bf16 v[30:33], v[134:137], v[204:207], v[30:33]
	v_mfma_f32_16x16x32_bf16 v[26:29], v[142:145], v[204:207], v[26:29]
	v_mfma_f32_16x16x32_bf16 v[14:17], v[134:137], v[212:215], v[14:17]
	v_mfma_f32_16x16x32_bf16 v[10:13], v[142:145], v[212:215], v[10:13]
	v_mfma_f32_16x16x32_bf16 v[54:57], v[162:165], v[178:181], v[54:57]
	v_mfma_f32_16x16x32_bf16 v[50:53], v[170:173], v[178:181], v[50:53]
	v_mfma_f32_16x16x32_bf16 v[38:41], v[162:165], v[186:189], v[38:41]
	v_mfma_f32_16x16x32_bf16 v[34:37], v[170:173], v[186:189], v[34:37]
	v_mfma_f32_16x16x32_bf16 v[22:25], v[162:165], v[200:203], v[22:25]
	v_mfma_f32_16x16x32_bf16 v[18:21], v[170:173], v[200:203], v[18:21]
	v_mfma_f32_16x16x32_bf16 v[6:9], v[162:165], v[208:211], v[6:9]
	v_mfma_f32_16x16x32_bf16 v[2:5], v[170:173], v[208:211], v[2:5]
	v_mfma_f32_16x16x32_bf16 v[54:57], v[166:169], v[182:185], v[54:57]
	v_mfma_f32_16x16x32_bf16 v[50:53], v[174:177], v[182:185], v[50:53]
	v_mfma_f32_16x16x32_bf16 v[38:41], v[166:169], v[196:199], v[38:41]
	v_mfma_f32_16x16x32_bf16 v[34:37], v[174:177], v[196:199], v[34:37]
	v_mfma_f32_16x16x32_bf16 v[22:25], v[166:169], v[204:207], v[22:25]
	v_mfma_f32_16x16x32_bf16 v[18:21], v[174:177], v[204:207], v[18:21]
	v_mfma_f32_16x16x32_bf16 v[6:9], v[166:169], v[212:215], v[6:9]
	v_mfma_f32_16x16x32_bf16 v[2:5], v[174:177], v[212:215], v[2:5]
	s_barrier
	s_setprio 0
	s_add_i32 s68, s68, 2
	s_add_u32 s28, s28, 0x100
	s_addc_u32 s29, s29, 0
	s_add_u32 s63, s63, 0x100
	s_addc_u32 s65, s65, 0
	s_cmp_gt_u32 s68, 61
	s_cbranch_scc0 .LBB0_1246
	s_and_b64 vcc, exec, s[14:15]
	s_cbranch_vccz .LBB0_1249
	s_barrier

.LBB0_1521:
	ds_read_b128 v[130:133], v169
	ds_read_b128 v[134:137], v169 offset:1024
	ds_read_b128 v[138:141], v169 offset:2048
	ds_read_b128 v[142:145], v169 offset:3072
	ds_read_b128 v[162:165], v170
	ds_read_b128 v[172:175], v170 offset:1024
	ds_read_b128 v[176:179], v170 offset:2048
	ds_read_b128 v[180:183], v170 offset:3072
	s_add_u32 s38, s2, 0xfff00080
	s_addc_u32 s39, s3, -1
	s_cmp_eq_u32 s69, 60
	s_cselect_b32 s45, s29, s39
	s_cselect_b32 s44, s65, s38
	s_cselect_b32 s39, s27, s68
	s_cselect_b32 s38, s66, s67
	v_lshl_add_u64 v[216:217], s[2:3], 0, v[154:155]
	s_add_i32 m0, s37, 0xc000
	ds_read_b128 v[184:187], v171
	ds_read_b128 v[188:191], v171 offset:1024
	ds_read_b128 v[192:195], v171 offset:2048
	ds_read_b128 v[196:199], v171 offset:3072
	ds_read_b128 v[200:203], v171 offset:4096
	ds_read_b128 v[204:207], v171 offset:5120
	ds_read_b128 v[208:211], v171 offset:6144
	ds_read_b128 v[212:215], v171 offset:7168
	global_load_lds_dwordx4 v[216:217], off
	v_lshl_add_u64 v[216:217], s[2:3], 0, v[156:157]
	s_add_i32 m0, s37, 0xe000
	s_nop 0
	global_load_lds_dwordx4 v[216:217], off
	s_setprio 1
	s_waitcnt vmcnt(8) lgkmcnt(0)
	s_barrier
	v_mfma_f32_16x16x32_bf16 v[126:129], v[130:133], v[184:187], v[126:129]
	v_mfma_f32_16x16x32_bf16 v[122:125], v[138:141], v[184:187], v[122:125]
	v_mfma_f32_16x16x32_bf16 v[114:117], v[130:133], v[192:195], v[114:117]
	v_mfma_f32_16x16x32_bf16 v[106:109], v[138:141], v[192:195], v[106:109]
	v_mfma_f32_16x16x32_bf16 v[98:101], v[130:133], v[200:203], v[98:101]
	v_mfma_f32_16x16x32_bf16 v[90:93], v[138:141], v[200:203], v[90:93]
	v_mfma_f32_16x16x32_bf16 v[82:85], v[130:133], v[208:211], v[82:85]
	v_mfma_f32_16x16x32_bf16 v[74:77], v[138:141], v[208:211], v[74:77]
	v_mfma_f32_16x16x32_bf16 v[126:129], v[134:137], v[188:191], v[126:129]
	v_mfma_f32_16x16x32_bf16 v[122:125], v[142:145], v[188:191], v[122:125]
	v_mfma_f32_16x16x32_bf16 v[114:117], v[134:137], v[196:199], v[114:117]
	v_mfma_f32_16x16x32_bf16 v[106:109], v[142:145], v[196:199], v[106:109]
	v_mfma_f32_16x16x32_bf16 v[98:101], v[134:137], v[204:207], v[98:101]
	v_mfma_f32_16x16x32_bf16 v[90:93], v[142:145], v[204:207], v[90:93]
	v_mfma_f32_16x16x32_bf16 v[82:85], v[134:137], v[212:215], v[82:85]
	v_mfma_f32_16x16x32_bf16 v[74:77], v[142:145], v[212:215], v[74:77]
	v_mfma_f32_16x16x32_bf16 v[118:121], v[162:165], v[184:187], v[118:121]
	v_mfma_f32_16x16x32_bf16 v[110:113], v[176:179], v[184:187], v[110:113]
	v_mfma_f32_16x16x32_bf16 v[102:105], v[162:165], v[192:195], v[102:105]
	v_mfma_f32_16x16x32_bf16 v[94:97], v[176:179], v[192:195], v[94:97]
	v_mfma_f32_16x16x32_bf16 v[86:89], v[162:165], v[200:203], v[86:89]
	v_mfma_f32_16x16x32_bf16 v[78:81], v[176:179], v[200:203], v[78:81]
	v_mfma_f32_16x16x32_bf16 v[70:73], v[162:165], v[208:211], v[70:73]
	v_mfma_f32_16x16x32_bf16 v[66:69], v[176:179], v[208:211], v[66:69]
	v_mfma_f32_16x16x32_bf16 v[118:121], v[172:175], v[188:191], v[118:121]
	v_mfma_f32_16x16x32_bf16 v[110:113], v[180:183], v[188:191], v[110:113]
	v_mfma_f32_16x16x32_bf16 v[102:105], v[172:175], v[196:199], v[102:105]
	v_mfma_f32_16x16x32_bf16 v[94:97], v[180:183], v[196:199], v[94:97]
	v_mfma_f32_16x16x32_bf16 v[86:89], v[172:175], v[204:207], v[86:89]
	v_mfma_f32_16x16x32_bf16 v[78:81], v[180:183], v[204:207], v[78:81]
	v_mfma_f32_16x16x32_bf16 v[70:73], v[172:175], v[212:215], v[70:73]
	v_mfma_f32_16x16x32_bf16 v[66:69], v[180:183], v[212:215], v[66:69]
	s_barrier
	s_setprio 0
	s_add_i32 s43, s57, s50
	v_lshl_add_u64 v[216:217], s[38:39], 0, v[150:151]
	s_mov_b32 m0, s43
	ds_read_b128 v[184:187], v171 offset:16384
	ds_read_b128 v[188:191], v171 offset:17408
	ds_read_b128 v[192:195], v171 offset:18432
	ds_read_b128 v[196:199], v171 offset:19456
	ds_read_b128 v[200:203], v171 offset:20480
	ds_read_b128 v[204:207], v171 offset:21504
	ds_read_b128 v[208:211], v171 offset:22528
	ds_read_b128 v[212:215], v171 offset:23552
	global_load_lds_dwordx4 v[216:217], off
	s_add_i32 m0, s43, 0x2000
	s_add_u32 s70, s38, 0x100000
	v_lshl_add_u64 v[218:219], s[38:39], 0, v[146:147]
	s_addc_u32 s71, s39, 0
	s_add_i32 s43, s58, s50
	global_load_lds_dwordx4 v[218:219], off
	v_lshl_add_u64 v[220:221], s[70:71], 0, v[150:151]
	s_mov_b32 m0, s43
	v_lshl_add_u64 v[222:223], s[44:45], 0, v[148:149]
	global_load_lds_dwordx4 v[220:221], off
	v_lshl_add_u64 v[220:221], s[70:71], 0, v[146:147]
	s_add_i32 m0, s43, 0x2000
	s_nop 0
	global_load_lds_dwordx4 v[220:221], off
	v_lshl_add_u64 v[220:221], s[44:45], 0, v[152:153]
	s_mov_b32 m0, s37
	s_nop 0
	global_load_lds_dwordx4 v[220:221], off
	s_mov_b32 m0, s51
	s_nop 0
	global_load_lds_dwordx4 v[222:223], off
	s_setprio 1
	s_waitcnt vmcnt(8) lgkmcnt(0)
	s_barrier
	v_mfma_f32_16x16x32_bf16 v[62:65], v[130:133], v[184:187], v[62:65]
	v_mfma_f32_16x16x32_bf16 v[58:61], v[138:141], v[184:187], v[58:61]
	v_mfma_f32_16x16x32_bf16 v[50:53], v[130:133], v[192:195], v[50:53]
	v_mfma_f32_16x16x32_bf16 v[42:45], v[138:141], v[192:195], v[42:45]
	v_mfma_f32_16x16x32_bf16 v[34:37], v[130:133], v[200:203], v[34:37]
	v_mfma_f32_16x16x32_bf16 v[26:29], v[138:141], v[200:203], v[26:29]
	v_mfma_f32_16x16x32_bf16 v[18:21], v[130:133], v[208:211], v[18:21]
	v_mfma_f32_16x16x32_bf16 v[10:13], v[138:141], v[208:211], v[10:13]
	v_mfma_f32_16x16x32_bf16 v[62:65], v[134:137], v[188:191], v[62:65]
	v_mfma_f32_16x16x32_bf16 v[58:61], v[142:145], v[188:191], v[58:61]
	v_mfma_f32_16x16x32_bf16 v[50:53], v[134:137], v[196:199], v[50:53]
	v_mfma_f32_16x16x32_bf16 v[42:45], v[142:145], v[196:199], v[42:45]
	v_mfma_f32_16x16x32_bf16 v[34:37], v[134:137], v[204:207], v[34:37]
	v_mfma_f32_16x16x32_bf16 v[26:29], v[142:145], v[204:207], v[26:29]
	v_mfma_f32_16x16x32_bf16 v[18:21], v[134:137], v[212:215], v[18:21]
	v_mfma_f32_16x16x32_bf16 v[10:13], v[142:145], v[212:215], v[10:13]
	v_mfma_f32_16x16x32_bf16 v[54:57], v[162:165], v[184:187], v[54:57]
	v_mfma_f32_16x16x32_bf16 v[46:49], v[176:179], v[184:187], v[46:49]
	v_mfma_f32_16x16x32_bf16 v[38:41], v[162:165], v[192:195], v[38:41]
	v_mfma_f32_16x16x32_bf16 v[30:33], v[176:179], v[192:195], v[30:33]
	v_mfma_f32_16x16x32_bf16 v[22:25], v[162:165], v[200:203], v[22:25]
	v_mfma_f32_16x16x32_bf16 v[14:17], v[176:179], v[200:203], v[14:17]
	v_mfma_f32_16x16x32_bf16 v[6:9], v[162:165], v[208:211], v[6:9]
	v_mfma_f32_16x16x32_bf16 v[2:5], v[176:179], v[208:211], v[2:5]
	v_mfma_f32_16x16x32_bf16 v[54:57], v[172:175], v[188:191], v[54:57]
	v_mfma_f32_16x16x32_bf16 v[46:49], v[180:183], v[188:191], v[46:49]
	v_mfma_f32_16x16x32_bf16 v[38:41], v[172:175], v[196:199], v[38:41]
	v_mfma_f32_16x16x32_bf16 v[30:33], v[180:183], v[196:199], v[30:33]
	v_mfma_f32_16x16x32_bf16 v[22:25], v[172:175], v[204:207], v[22:25]
	v_mfma_f32_16x16x32_bf16 v[14:17], v[180:183], v[204:207], v[14:17]
	v_mfma_f32_16x16x32_bf16 v[6:9], v[172:175], v[212:215], v[6:9]
	v_mfma_f32_16x16x32_bf16 v[2:5], v[180:183], v[212:215], v[2:5]
	s_barrier
	s_setprio 0
	s_add_i32 s43, 0, 0x18000
	s_add_i32 s70, 0, 0x1c000
	v_add_u32_e32 v142, s43, v167
	v_add_u32_e32 v180, s70, v167
	ds_read_b128 v[130:133], v142
	ds_read_b128 v[134:137], v142 offset:1024
	ds_read_b128 v[138:141], v142 offset:2048
	ds_read_b128 v[142:145], v142 offset:3072
	ds_read_b128 v[162:165], v180
	ds_read_b128 v[172:175], v180 offset:1024
	ds_read_b128 v[176:179], v180 offset:2048
	ds_read_b128 v[180:183], v180 offset:3072
	s_add_u32 s44, s44, 0x100000
	s_addc_u32 s45, s45, 0
	s_mov_b32 m0, s52
	v_lshl_add_u64 v[224:225], s[44:45], 0, v[152:153]
	ds_read_b128 v[184:187], v171 offset:32768
	ds_read_b128 v[188:191], v171 offset:33792
	ds_read_b128 v[192:195], v171 offset:34816
	ds_read_b128 v[196:199], v171 offset:35840
	ds_read_b128 v[200:203], v171 offset:36864
	ds_read_b128 v[204:207], v171 offset:37888
	ds_read_b128 v[208:211], v171 offset:38912
	ds_read_b128 v[212:215], v171 offset:39936
	global_load_lds_dwordx4 v[224:225], off
	v_lshl_add_u64 v[224:225], s[44:45], 0, v[148:149]
	s_mov_b32 m0, s53
	s_nop 0
	global_load_lds_dwordx4 v[224:225], off
	s_setprio 1
	s_waitcnt vmcnt(8) lgkmcnt(0)
	s_barrier
	v_mfma_f32_16x16x32_bf16 v[126:129], v[130:133], v[184:187], v[126:129]
	v_mfma_f32_16x16x32_bf16 v[122:125], v[138:141], v[184:187], v[122:125]
	v_mfma_f32_16x16x32_bf16 v[114:117], v[130:133], v[192:195], v[114:117]
	v_mfma_f32_16x16x32_bf16 v[106:109], v[138:141], v[192:195], v[106:109]
	v_mfma_f32_16x16x32_bf16 v[98:101], v[130:133], v[200:203], v[98:101]
	v_mfma_f32_16x16x32_bf16 v[90:93], v[138:141], v[200:203], v[90:93]
	v_mfma_f32_16x16x32_bf16 v[82:85], v[130:133], v[208:211], v[82:85]
	v_mfma_f32_16x16x32_bf16 v[74:77], v[138:141], v[208:211], v[74:77]
	v_mfma_f32_16x16x32_bf16 v[126:129], v[134:137], v[188:191], v[126:129]
	v_mfma_f32_16x16x32_bf16 v[122:125], v[142:145], v[188:191], v[122:125]
	v_mfma_f32_16x16x32_bf16 v[114:117], v[134:137], v[196:199], v[114:117]
	v_mfma_f32_16x16x32_bf16 v[106:109], v[142:145], v[196:199], v[106:109]
	v_mfma_f32_16x16x32_bf16 v[98:101], v[134:137], v[204:207], v[98:101]
	v_mfma_f32_16x16x32_bf16 v[90:93], v[142:145], v[204:207], v[90:93]
	v_mfma_f32_16x16x32_bf16 v[82:85], v[134:137], v[212:215], v[82:85]
	v_mfma_f32_16x16x32_bf16 v[74:77], v[142:145], v[212:215], v[74:77]
	v_mfma_f32_16x16x32_bf16 v[118:121], v[162:165], v[184:187], v[118:121]
	v_mfma_f32_16x16x32_bf16 v[110:113], v[176:179], v[184:187], v[110:113]
	v_mfma_f32_16x16x32_bf16 v[102:105], v[162:165], v[192:195], v[102:105]
	v_mfma_f32_16x16x32_bf16 v[94:97], v[176:179], v[192:195], v[94:97]
	v_mfma_f32_16x16x32_bf16 v[86:89], v[162:165], v[200:203], v[86:89]
	v_mfma_f32_16x16x32_bf16 v[78:81], v[176:179], v[200:203], v[78:81]
	v_mfma_f32_16x16x32_bf16 v[70:73], v[162:165], v[208:211], v[70:73]
	v_mfma_f32_16x16x32_bf16 v[66:69], v[176:179], v[208:211], v[66:69]
	v_mfma_f32_16x16x32_bf16 v[118:121], v[172:175], v[188:191], v[118:121]
	v_mfma_f32_16x16x32_bf16 v[110:113], v[180:183], v[188:191], v[110:113]
	v_mfma_f32_16x16x32_bf16 v[102:105], v[172:175], v[196:199], v[102:105]
	v_mfma_f32_16x16x32_bf16 v[94:97], v[180:183], v[196:199], v[94:97]
	v_mfma_f32_16x16x32_bf16 v[86:89], v[172:175], v[204:207], v[86:89]
	v_mfma_f32_16x16x32_bf16 v[78:81], v[180:183], v[204:207], v[78:81]
	v_mfma_f32_16x16x32_bf16 v[70:73], v[172:175], v[212:215], v[70:73]
	v_mfma_f32_16x16x32_bf16 v[66:69], v[180:183], v[212:215], v[66:69]
	s_barrier
	s_setprio 0
	s_add_i32 s43, s43, s50
	v_lshl_add_u64 v[216:217], v[216:217], 0, s[16:17]
	s_mov_b32 m0, s43
	ds_read_b128 v[184:187], v171 offset:49152
	ds_read_b128 v[188:191], v171 offset:50176
	ds_read_b128 v[192:195], v171 offset:51200
	ds_read_b128 v[196:199], v171 offset:52224
	ds_read_b128 v[200:203], v171 offset:53248
	ds_read_b128 v[204:207], v171 offset:54272
	ds_read_b128 v[208:211], v171 offset:55296
	ds_read_b128 v[212:215], v171 offset:56320
	global_load_lds_dwordx4 v[216:217], off
	s_add_i32 m0, s43, 0x2000
	s_add_u32 s38, s38, 0x100080
	v_lshl_add_u64 v[216:217], v[218:219], 0, s[16:17]
	s_addc_u32 s39, s39, 0
	s_add_i32 s43, s70, s50
	global_load_lds_dwordx4 v[216:217], off
	v_lshl_add_u64 v[216:217], s[38:39], 0, v[150:151]
	s_mov_b32 m0, s43
	s_nop 0
	global_load_lds_dwordx4 v[216:217], off
	v_lshl_add_u64 v[216:217], s[38:39], 0, v[146:147]
	s_add_i32 m0, s43, 0x2000
	s_nop 0
	global_load_lds_dwordx4 v[216:217], off
	v_lshl_add_u64 v[216:217], v[220:221], 0, s[16:17]
	s_mov_b32 m0, s55
	s_nop 0
	global_load_lds_dwordx4 v[216:217], off
	v_lshl_add_u64 v[216:217], v[222:223], 0, s[16:17]
	s_mov_b32 m0, s56
	s_nop 0
	global_load_lds_dwordx4 v[216:217], off
	s_setprio 1
	s_waitcnt vmcnt(8) lgkmcnt(0)
	s_barrier
	v_mfma_f32_16x16x32_bf16 v[62:65], v[130:133], v[184:187], v[62:65]
	v_mfma_f32_16x16x32_bf16 v[58:61], v[138:141], v[184:187], v[58:61]
	v_mfma_f32_16x16x32_bf16 v[50:53], v[130:133], v[192:195], v[50:53]
	v_mfma_f32_16x16x32_bf16 v[42:45], v[138:141], v[192:195], v[42:45]
	v_mfma_f32_16x16x32_bf16 v[34:37], v[130:133], v[200:203], v[34:37]
	v_mfma_f32_16x16x32_bf16 v[26:29], v[138:141], v[200:203], v[26:29]
	v_mfma_f32_16x16x32_bf16 v[18:21], v[130:133], v[208:211], v[18:21]
	v_mfma_f32_16x16x32_bf16 v[10:13], v[138:141], v[208:211], v[10:13]
	v_mfma_f32_16x16x32_bf16 v[62:65], v[134:137], v[188:191], v[62:65]
	v_mfma_f32_16x16x32_bf16 v[58:61], v[142:145], v[188:191], v[58:61]
	v_mfma_f32_16x16x32_bf16 v[50:53], v[134:137], v[196:199], v[50:53]
	v_mfma_f32_16x16x32_bf16 v[42:45], v[142:145], v[196:199], v[42:45]
	v_mfma_f32_16x16x32_bf16 v[34:37], v[134:137], v[204:207], v[34:37]
	v_mfma_f32_16x16x32_bf16 v[26:29], v[142:145], v[204:207], v[26:29]
	v_mfma_f32_16x16x32_bf16 v[18:21], v[134:137], v[212:215], v[18:21]
	v_mfma_f32_16x16x32_bf16 v[10:13], v[142:145], v[212:215], v[10:13]
	v_mfma_f32_16x16x32_bf16 v[54:57], v[162:165], v[184:187], v[54:57]
	v_mfma_f32_16x16x32_bf16 v[46:49], v[176:179], v[184:187], v[46:49]
	v_mfma_f32_16x16x32_bf16 v[38:41], v[162:165], v[192:195], v[38:41]
	v_mfma_f32_16x16x32_bf16 v[30:33], v[176:179], v[192:195], v[30:33]
	v_mfma_f32_16x16x32_bf16 v[22:25], v[162:165], v[200:203], v[22:25]
	v_mfma_f32_16x16x32_bf16 v[14:17], v[176:179], v[200:203], v[14:17]
	v_mfma_f32_16x16x32_bf16 v[6:9], v[162:165], v[208:211], v[6:9]
	v_mfma_f32_16x16x32_bf16 v[2:5], v[176:179], v[208:211], v[2:5]
	v_mfma_f32_16x16x32_bf16 v[54:57], v[172:175], v[188:191], v[54:57]
	v_mfma_f32_16x16x32_bf16 v[46:49], v[180:183], v[188:191], v[46:49]
	v_mfma_f32_16x16x32_bf16 v[38:41], v[172:175], v[196:199], v[38:41]
	v_mfma_f32_16x16x32_bf16 v[30:33], v[180:183], v[196:199], v[30:33]
	v_mfma_f32_16x16x32_bf16 v[22:25], v[172:175], v[204:207], v[22:25]
	v_mfma_f32_16x16x32_bf16 v[14:17], v[180:183], v[204:207], v[14:17]
	v_mfma_f32_16x16x32_bf16 v[6:9], v[172:175], v[212:215], v[6:9]
	v_mfma_f32_16x16x32_bf16 v[2:5], v[180:183], v[212:215], v[2:5]
	s_barrier
	s_setprio 0
	s_add_i32 s69, s69, 2
	s_add_u32 s2, s2, 0x100
	s_addc_u32 s3, s3, 0
	s_add_u32 s67, s67, 0x100
	s_addc_u32 s68, s68, 0
	s_cmp_gt_u32 s69, 61
	s_cbranch_scc0 .LBB0_1521
	s_and_b64 vcc, exec, s[18:19]
	s_cbranch_vccz .LBB0_1524
	s_barrier

.LBB0_1697:
	ds_read_b128 v[130:133], v238
	ds_read_b128 v[134:137], v238 offset:1024
	ds_read_b128 v[138:141], v238 offset:2048
	ds_read_b128 v[142:145], v238 offset:3072
	ds_read_b128 v[146:149], v239
	ds_read_b128 v[150:153], v239 offset:1024
	ds_read_b128 v[154:157], v239 offset:2048
	ds_read_b128 v[158:161], v239 offset:3072
	s_add_u32 s56, s2, 0x100
	s_addc_u32 s57, s3, 0
	s_cmp_eq_u32 s91, 28
	s_cselect_b32 s61, s49, s57
	s_cselect_b32 s60, s87, s56
	s_cselect_b32 s59, s47, s90
	s_cselect_b32 s58, s88, s89
	v_lshl_add_u64 v[194:195], s[2:3], 0, v[210:211]
	s_add_i32 m0, s55, 0xc000
	ds_read_b128 v[162:165], v240
	ds_read_b128 v[166:169], v240 offset:1024
	ds_read_b128 v[170:173], v240 offset:2048
	ds_read_b128 v[174:177], v240 offset:3072
	ds_read_b128 v[178:181], v240 offset:4096
	ds_read_b128 v[182:185], v240 offset:5120
	ds_read_b128 v[186:189], v240 offset:6144
	ds_read_b128 v[190:193], v240 offset:7168
	global_load_lds_dwordx4 v[194:195], off
	v_lshl_add_u64 v[194:195], s[2:3], 0, v[212:213]
	s_add_i32 m0, s55, 0xe000
	s_nop 0
	global_load_lds_dwordx4 v[194:195], off
	s_setprio 1
	s_waitcnt vmcnt(8) lgkmcnt(0)
	s_barrier
	v_mfma_i32_16x16x64_i8 v[126:129], v[130:133], v[162:165], v[126:129]
	v_mfma_i32_16x16x64_i8 v[122:125], v[138:141], v[162:165], v[122:125]
	v_mfma_i32_16x16x64_i8 v[118:121], v[130:133], v[170:173], v[118:121]
	v_mfma_i32_16x16x64_i8 v[110:113], v[138:141], v[170:173], v[110:113]
	v_mfma_i32_16x16x64_i8 v[78:81], v[130:133], v[178:181], v[78:81]
	v_mfma_i32_16x16x64_i8 v[30:33], v[138:141], v[178:181], v[30:33]
	v_mfma_i32_16x16x64_i8 v[74:77], v[130:133], v[186:189], v[74:77]
	v_mfma_i32_16x16x64_i8 v[26:29], v[138:141], v[186:189], v[26:29]
	v_mfma_i32_16x16x64_i8 v[126:129], v[134:137], v[166:169], v[126:129]
	v_mfma_i32_16x16x64_i8 v[122:125], v[142:145], v[166:169], v[122:125]
	v_mfma_i32_16x16x64_i8 v[118:121], v[134:137], v[174:177], v[118:121]
	v_mfma_i32_16x16x64_i8 v[110:113], v[142:145], v[174:177], v[110:113]
	v_mfma_i32_16x16x64_i8 v[78:81], v[134:137], v[182:185], v[78:81]
	v_mfma_i32_16x16x64_i8 v[30:33], v[142:145], v[182:185], v[30:33]
	v_mfma_i32_16x16x64_i8 v[74:77], v[134:137], v[190:193], v[74:77]
	v_mfma_i32_16x16x64_i8 v[26:29], v[142:145], v[190:193], v[26:29]
	v_mfma_i32_16x16x64_i8 v[102:105], v[146:149], v[162:165], v[102:105]
	v_mfma_i32_16x16x64_i8 v[98:101], v[154:157], v[162:165], v[98:101]
	v_mfma_i32_16x16x64_i8 v[94:97], v[146:149], v[170:173], v[94:97]
	v_mfma_i32_16x16x64_i8 v[90:93], v[154:157], v[170:173], v[90:93]
	v_mfma_i32_16x16x64_i8 v[70:73], v[146:149], v[178:181], v[70:73]
	v_mfma_i32_16x16x64_i8 v[22:25], v[154:157], v[178:181], v[22:25]
	v_mfma_i32_16x16x64_i8 v[66:69], v[146:149], v[186:189], v[66:69]
	v_mfma_i32_16x16x64_i8 v[18:21], v[154:157], v[186:189], v[18:21]
	v_mfma_i32_16x16x64_i8 v[102:105], v[150:153], v[166:169], v[102:105]
	v_mfma_i32_16x16x64_i8 v[98:101], v[158:161], v[166:169], v[98:101]
	v_mfma_i32_16x16x64_i8 v[94:97], v[150:153], v[174:177], v[94:97]
	v_mfma_i32_16x16x64_i8 v[90:93], v[158:161], v[174:177], v[90:93]
	v_mfma_i32_16x16x64_i8 v[70:73], v[150:153], v[182:185], v[70:73]
	v_mfma_i32_16x16x64_i8 v[22:25], v[158:161], v[182:185], v[22:25]
	v_mfma_i32_16x16x64_i8 v[66:69], v[150:153], v[190:193], v[66:69]
	v_mfma_i32_16x16x64_i8 v[18:21], v[158:161], v[190:193], v[18:21]
	s_barrier
	s_setprio 0
	s_add_i32 s2, s83, s66
	v_lshl_add_u64 v[194:195], s[58:59], 0, v[206:207]
	s_mov_b32 m0, s2
	ds_read_b128 v[162:165], v240 offset:16384
	ds_read_b128 v[166:169], v240 offset:17408
	ds_read_b128 v[170:173], v240 offset:18432
	ds_read_b128 v[174:177], v240 offset:19456
	ds_read_b128 v[178:181], v240 offset:20480
	ds_read_b128 v[182:185], v240 offset:21504
	ds_read_b128 v[186:189], v240 offset:22528
	ds_read_b128 v[190:193], v240 offset:23552
	global_load_lds_dwordx4 v[194:195], off
	s_add_i32 m0, s2, 0x2000
	s_add_u32 s2, s58, 0x80000
	v_lshl_add_u64 v[196:197], s[58:59], 0, v[202:203]
	s_addc_u32 s3, s59, 0
	s_add_i32 s43, s84, s66
	global_load_lds_dwordx4 v[196:197], off
	v_lshl_add_u64 v[198:199], s[2:3], 0, v[206:207]
	s_mov_b32 m0, s43
	v_lshl_add_u64 v[200:201], s[60:61], 0, v[204:205]
	global_load_lds_dwordx4 v[198:199], off
	v_lshl_add_u64 v[198:199], s[2:3], 0, v[202:203]
	s_add_i32 m0, s43, 0x2000
	s_nop 0
	global_load_lds_dwordx4 v[198:199], off
	v_lshl_add_u64 v[198:199], s[60:61], 0, v[208:209]
	s_mov_b32 m0, s55
	s_nop 0
	global_load_lds_dwordx4 v[198:199], off
	s_mov_b32 m0, s68
	s_nop 0
	global_load_lds_dwordx4 v[200:201], off
	s_setprio 1
	s_waitcnt vmcnt(8) lgkmcnt(0)
	s_barrier
	v_mfma_i32_16x16x64_i8 v[62:65], v[130:133], v[162:165], v[62:65]
	v_mfma_i32_16x16x64_i8 v[14:17], v[138:141], v[162:165], v[14:17]
	v_mfma_i32_16x16x64_i8 v[58:61], v[130:133], v[170:173], v[58:61]
	v_mfma_i32_16x16x64_i8 v[10:13], v[138:141], v[170:173], v[10:13]
	v_mfma_i32_16x16x64_i8 v[114:117], v[130:133], v[178:181], v[114:117]
	v_mfma_i32_16x16x64_i8 v[106:109], v[138:141], v[178:181], v[106:109]
	v_mfma_i32_16x16x64_i8 v[86:89], v[130:133], v[186:189], v[86:89]
	v_mfma_i32_16x16x64_i8 v[82:85], v[138:141], v[186:189], v[82:85]
	v_mfma_i32_16x16x64_i8 v[62:65], v[134:137], v[166:169], v[62:65]
	v_mfma_i32_16x16x64_i8 v[14:17], v[142:145], v[166:169], v[14:17]
	v_mfma_i32_16x16x64_i8 v[58:61], v[134:137], v[174:177], v[58:61]
	v_mfma_i32_16x16x64_i8 v[10:13], v[142:145], v[174:177], v[10:13]
	v_mfma_i32_16x16x64_i8 v[114:117], v[134:137], v[182:185], v[114:117]
	v_mfma_i32_16x16x64_i8 v[106:109], v[142:145], v[182:185], v[106:109]
	v_mfma_i32_16x16x64_i8 v[86:89], v[134:137], v[190:193], v[86:89]
	v_mfma_i32_16x16x64_i8 v[82:85], v[142:145], v[190:193], v[82:85]
	v_mfma_i32_16x16x64_i8 v[50:53], v[146:149], v[162:165], v[50:53]
	v_mfma_i32_16x16x64_i8 v[6:9], v[154:157], v[162:165], v[6:9]
	v_mfma_i32_16x16x64_i8 v[42:45], v[146:149], v[170:173], v[42:45]
	v_mfma_i32_16x16x64_i8 v[2:5], v[154:157], v[170:173], v[2:5]
	v_mfma_i32_16x16x64_i8 v[54:57], v[146:149], v[178:181], v[54:57]
	v_mfma_i32_16x16x64_i8 v[46:49], v[154:157], v[178:181], v[46:49]
	v_mfma_i32_16x16x64_i8 v[38:41], v[146:149], v[186:189], v[38:41]
	v_mfma_i32_16x16x64_i8 v[34:37], v[154:157], v[186:189], v[34:37]
	v_mfma_i32_16x16x64_i8 v[50:53], v[150:153], v[166:169], v[50:53]
	v_mfma_i32_16x16x64_i8 v[6:9], v[158:161], v[166:169], v[6:9]
	v_mfma_i32_16x16x64_i8 v[42:45], v[150:153], v[174:177], v[42:45]
	v_mfma_i32_16x16x64_i8 v[2:5], v[158:161], v[174:177], v[2:5]
	v_mfma_i32_16x16x64_i8 v[54:57], v[150:153], v[182:185], v[54:57]
	v_mfma_i32_16x16x64_i8 v[46:49], v[158:161], v[182:185], v[46:49]
	v_mfma_i32_16x16x64_i8 v[38:41], v[150:153], v[190:193], v[38:41]
	v_mfma_i32_16x16x64_i8 v[34:37], v[158:161], v[190:193], v[34:37]
	s_barrier
	s_setprio 0
	s_add_i32 s43, 0, 0x18000
	s_add_i32 s92, 0, 0x1c000
	v_add_u32_e32 v142, s43, v237
	v_add_u32_e32 v158, s92, v237
	ds_read_b128 v[130:133], v142
	ds_read_b128 v[134:137], v142 offset:1024
	ds_read_b128 v[138:141], v142 offset:2048
	ds_read_b128 v[142:145], v142 offset:3072
	ds_read_b128 v[146:149], v158
	ds_read_b128 v[150:153], v158 offset:1024
	ds_read_b128 v[154:157], v158 offset:2048
	ds_read_b128 v[158:161], v158 offset:3072
	s_add_u32 s2, s60, 0x4000
	s_addc_u32 s3, s61, 0
	s_mov_b32 m0, s69
	v_lshl_add_u64 v[220:221], s[2:3], 0, v[208:209]
	ds_read_b128 v[162:165], v240 offset:32768
	ds_read_b128 v[166:169], v240 offset:33792
	ds_read_b128 v[170:173], v240 offset:34816
	ds_read_b128 v[174:177], v240 offset:35840
	ds_read_b128 v[178:181], v240 offset:36864
	ds_read_b128 v[182:185], v240 offset:37888
	ds_read_b128 v[186:189], v240 offset:38912
	ds_read_b128 v[190:193], v240 offset:39936
	global_load_lds_dwordx4 v[220:221], off
	v_lshl_add_u64 v[220:221], s[2:3], 0, v[204:205]
	s_mov_b32 m0, s70
	s_nop 0
	global_load_lds_dwordx4 v[220:221], off
	s_setprio 1
	s_waitcnt vmcnt(8) lgkmcnt(0)
	s_barrier
	v_mfma_i32_16x16x64_i8 v[126:129], v[130:133], v[162:165], v[126:129]
	v_mfma_i32_16x16x64_i8 v[122:125], v[138:141], v[162:165], v[122:125]
	v_mfma_i32_16x16x64_i8 v[118:121], v[130:133], v[170:173], v[118:121]
	v_mfma_i32_16x16x64_i8 v[110:113], v[138:141], v[170:173], v[110:113]
	v_mfma_i32_16x16x64_i8 v[78:81], v[130:133], v[178:181], v[78:81]
	v_mfma_i32_16x16x64_i8 v[30:33], v[138:141], v[178:181], v[30:33]
	v_mfma_i32_16x16x64_i8 v[74:77], v[130:133], v[186:189], v[74:77]
	v_mfma_i32_16x16x64_i8 v[26:29], v[138:141], v[186:189], v[26:29]
	v_mfma_i32_16x16x64_i8 v[126:129], v[134:137], v[166:169], v[126:129]
	v_mfma_i32_16x16x64_i8 v[122:125], v[142:145], v[166:169], v[122:125]
	v_mfma_i32_16x16x64_i8 v[118:121], v[134:137], v[174:177], v[118:121]
	v_mfma_i32_16x16x64_i8 v[110:113], v[142:145], v[174:177], v[110:113]
	v_mfma_i32_16x16x64_i8 v[78:81], v[134:137], v[182:185], v[78:81]
	v_mfma_i32_16x16x64_i8 v[30:33], v[142:145], v[182:185], v[30:33]
	v_mfma_i32_16x16x64_i8 v[74:77], v[134:137], v[190:193], v[74:77]
	v_mfma_i32_16x16x64_i8 v[26:29], v[142:145], v[190:193], v[26:29]
	v_mfma_i32_16x16x64_i8 v[102:105], v[146:149], v[162:165], v[102:105]
	v_mfma_i32_16x16x64_i8 v[98:101], v[154:157], v[162:165], v[98:101]
	v_mfma_i32_16x16x64_i8 v[94:97], v[146:149], v[170:173], v[94:97]
	v_mfma_i32_16x16x64_i8 v[90:93], v[154:157], v[170:173], v[90:93]
	v_mfma_i32_16x16x64_i8 v[70:73], v[146:149], v[178:181], v[70:73]
	v_mfma_i32_16x16x64_i8 v[22:25], v[154:157], v[178:181], v[22:25]
	v_mfma_i32_16x16x64_i8 v[66:69], v[146:149], v[186:189], v[66:69]
	v_mfma_i32_16x16x64_i8 v[18:21], v[154:157], v[186:189], v[18:21]
	v_mfma_i32_16x16x64_i8 v[102:105], v[150:153], v[166:169], v[102:105]
	v_mfma_i32_16x16x64_i8 v[98:101], v[158:161], v[166:169], v[98:101]
	v_mfma_i32_16x16x64_i8 v[94:97], v[150:153], v[174:177], v[94:97]
	v_mfma_i32_16x16x64_i8 v[90:93], v[158:161], v[174:177], v[90:93]
	v_mfma_i32_16x16x64_i8 v[70:73], v[150:153], v[182:185], v[70:73]
	v_mfma_i32_16x16x64_i8 v[22:25], v[158:161], v[182:185], v[22:25]
	v_mfma_i32_16x16x64_i8 v[66:69], v[150:153], v[190:193], v[66:69]
	v_mfma_i32_16x16x64_i8 v[18:21], v[158:161], v[190:193], v[18:21]
	s_barrier
	s_setprio 0
	s_add_i32 s2, s43, s66
	v_lshl_add_u64 v[194:195], v[194:195], 0, s[36:37]
	s_mov_b32 m0, s2
	ds_read_b128 v[162:165], v240 offset:49152
	ds_read_b128 v[166:169], v240 offset:50176
	ds_read_b128 v[170:173], v240 offset:51200
	ds_read_b128 v[174:177], v240 offset:52224
	ds_read_b128 v[178:181], v240 offset:53248
	ds_read_b128 v[182:185], v240 offset:54272
	ds_read_b128 v[186:189], v240 offset:55296
	ds_read_b128 v[190:193], v240 offset:56320
	global_load_lds_dwordx4 v[194:195], off
	s_add_i32 m0, s2, 0x2000
	s_add_u32 s2, s58, 0x80080
	v_lshl_add_u64 v[194:195], v[196:197], 0, s[36:37]
	s_addc_u32 s3, s59, 0
	s_add_i32 s43, s92, s66
	global_load_lds_dwordx4 v[194:195], off
	v_lshl_add_u64 v[194:195], s[2:3], 0, v[206:207]
	s_mov_b32 m0, s43
	s_nop 0
	global_load_lds_dwordx4 v[194:195], off
	v_lshl_add_u64 v[194:195], s[2:3], 0, v[202:203]
	s_add_i32 m0, s43, 0x2000
	s_nop 0
	global_load_lds_dwordx4 v[194:195], off
	v_lshl_add_u64 v[194:195], v[198:199], 0, s[36:37]
	s_mov_b32 m0, s77
	s_nop 0
	global_load_lds_dwordx4 v[194:195], off
	v_lshl_add_u64 v[194:195], v[200:201], 0, s[36:37]
	s_mov_b32 m0, s78
	s_nop 0
	global_load_lds_dwordx4 v[194:195], off
	s_setprio 1
	s_waitcnt vmcnt(8) lgkmcnt(0)
	s_barrier
	v_mfma_i32_16x16x64_i8 v[62:65], v[130:133], v[162:165], v[62:65]
	v_mfma_i32_16x16x64_i8 v[14:17], v[138:141], v[162:165], v[14:17]
	v_mfma_i32_16x16x64_i8 v[58:61], v[130:133], v[170:173], v[58:61]
	v_mfma_i32_16x16x64_i8 v[10:13], v[138:141], v[170:173], v[10:13]
	v_mfma_i32_16x16x64_i8 v[114:117], v[130:133], v[178:181], v[114:117]
	v_mfma_i32_16x16x64_i8 v[106:109], v[138:141], v[178:181], v[106:109]
	v_mfma_i32_16x16x64_i8 v[86:89], v[130:133], v[186:189], v[86:89]
	v_mfma_i32_16x16x64_i8 v[82:85], v[138:141], v[186:189], v[82:85]
	v_mfma_i32_16x16x64_i8 v[62:65], v[134:137], v[166:169], v[62:65]
	v_mfma_i32_16x16x64_i8 v[14:17], v[142:145], v[166:169], v[14:17]
	v_mfma_i32_16x16x64_i8 v[58:61], v[134:137], v[174:177], v[58:61]
	v_mfma_i32_16x16x64_i8 v[10:13], v[142:145], v[174:177], v[10:13]
	v_mfma_i32_16x16x64_i8 v[114:117], v[134:137], v[182:185], v[114:117]
	v_mfma_i32_16x16x64_i8 v[106:109], v[142:145], v[182:185], v[106:109]
	v_mfma_i32_16x16x64_i8 v[86:89], v[134:137], v[190:193], v[86:89]
	v_mfma_i32_16x16x64_i8 v[82:85], v[142:145], v[190:193], v[82:85]
	v_mfma_i32_16x16x64_i8 v[50:53], v[146:149], v[162:165], v[50:53]
	v_mfma_i32_16x16x64_i8 v[6:9], v[154:157], v[162:165], v[6:9]
	v_mfma_i32_16x16x64_i8 v[42:45], v[146:149], v[170:173], v[42:45]
	v_mfma_i32_16x16x64_i8 v[2:5], v[154:157], v[170:173], v[2:5]
	v_mfma_i32_16x16x64_i8 v[54:57], v[146:149], v[178:181], v[54:57]
	v_mfma_i32_16x16x64_i8 v[46:49], v[154:157], v[178:181], v[46:49]
	v_mfma_i32_16x16x64_i8 v[38:41], v[146:149], v[186:189], v[38:41]
	v_mfma_i32_16x16x64_i8 v[34:37], v[154:157], v[186:189], v[34:37]
	v_mfma_i32_16x16x64_i8 v[50:53], v[150:153], v[166:169], v[50:53]
	v_mfma_i32_16x16x64_i8 v[6:9], v[158:161], v[166:169], v[6:9]
	v_mfma_i32_16x16x64_i8 v[42:45], v[150:153], v[174:177], v[42:45]
	v_mfma_i32_16x16x64_i8 v[2:5], v[158:161], v[174:177], v[2:5]
	v_mfma_i32_16x16x64_i8 v[54:57], v[150:153], v[182:185], v[54:57]
	v_mfma_i32_16x16x64_i8 v[46:49], v[158:161], v[182:185], v[46:49]
	v_mfma_i32_16x16x64_i8 v[38:41], v[150:153], v[190:193], v[38:41]
	v_mfma_i32_16x16x64_i8 v[34:37], v[158:161], v[190:193], v[34:37]
	s_barrier
	s_setprio 0
	s_add_i32 s91, s91, 2
	s_add_u32 s89, s89, 0x100
	s_addc_u32 s90, s90, 0
	s_cmp_gt_u32 s91, 29
	s_mov_b64 s[2:3], s[56:57]
	s_cbranch_scc0 .LBB0_1697
	s_and_b64 vcc, exec, s[38:39]
	s_cbranch_vccz .LBB0_1700
	s_barrier

.LBB0_1951:
	ds_read_b128 v[130:133], v167
	ds_read_b128 v[134:137], v167 offset:1024
	ds_read_b128 v[138:141], v167 offset:2048
	ds_read_b128 v[142:145], v167 offset:3072
	ds_read_b128 v[170:173], v168
	ds_read_b128 v[174:177], v168 offset:1024
	ds_read_b128 v[178:181], v168 offset:2048
	ds_read_b128 v[182:185], v168 offset:3072
	s_add_u32 s38, s36, 0x100
	s_addc_u32 s39, s37, 0
	s_cmpk_eq_i32 s77, 0x52
	s_cselect_b32 s47, s3, s39
	s_cselect_b32 s46, s2, s38
	s_cselect_b32 s45, s35, s76
	s_cselect_b32 s44, s34, s75
	v_lshl_add_u64 v[162:163], s[36:37], 0, v[154:155]
	s_add_i32 m0, s52, 0xc000
	ds_read_b128 v[186:189], v169
	ds_read_b128 v[190:193], v169 offset:1024
	ds_read_b128 v[194:197], v169 offset:2048
	ds_read_b128 v[198:201], v169 offset:3072
	ds_read_b128 v[202:205], v169 offset:4096
	ds_read_b128 v[206:209], v169 offset:5120
	ds_read_b128 v[210:213], v169 offset:6144
	ds_read_b128 v[214:217], v169 offset:7168
	global_load_lds_dwordx4 v[162:163], off
	v_lshl_add_u64 v[162:163], s[36:37], 0, v[156:157]
	s_add_i32 m0, s52, 0xe000
	s_nop 0
	global_load_lds_dwordx4 v[162:163], off
	s_setprio 1
	s_waitcnt vmcnt(8) lgkmcnt(0)
	s_barrier
	v_mfma_i32_16x16x64_i8 v[126:129], v[130:133], v[186:189], v[126:129]
	v_mfma_i32_16x16x64_i8 v[122:125], v[138:141], v[186:189], v[122:125]
	v_mfma_i32_16x16x64_i8 v[110:113], v[130:133], v[194:197], v[110:113]
	v_mfma_i32_16x16x64_i8 v[106:109], v[138:141], v[194:197], v[106:109]
	v_mfma_i32_16x16x64_i8 v[94:97], v[130:133], v[202:205], v[94:97]
	v_mfma_i32_16x16x64_i8 v[90:93], v[138:141], v[202:205], v[90:93]
	v_mfma_i32_16x16x64_i8 v[78:81], v[130:133], v[210:213], v[78:81]
	v_mfma_i32_16x16x64_i8 v[74:77], v[138:141], v[210:213], v[74:77]
	v_mfma_i32_16x16x64_i8 v[126:129], v[134:137], v[190:193], v[126:129]
	v_mfma_i32_16x16x64_i8 v[122:125], v[142:145], v[190:193], v[122:125]
	v_mfma_i32_16x16x64_i8 v[110:113], v[134:137], v[198:201], v[110:113]
	v_mfma_i32_16x16x64_i8 v[106:109], v[142:145], v[198:201], v[106:109]
	v_mfma_i32_16x16x64_i8 v[94:97], v[134:137], v[206:209], v[94:97]
	v_mfma_i32_16x16x64_i8 v[90:93], v[142:145], v[206:209], v[90:93]
	v_mfma_i32_16x16x64_i8 v[78:81], v[134:137], v[214:217], v[78:81]
	v_mfma_i32_16x16x64_i8 v[74:77], v[142:145], v[214:217], v[74:77]
	v_mfma_i32_16x16x64_i8 v[118:121], v[170:173], v[186:189], v[118:121]
	v_mfma_i32_16x16x64_i8 v[114:117], v[178:181], v[186:189], v[114:117]
	v_mfma_i32_16x16x64_i8 v[102:105], v[170:173], v[194:197], v[102:105]
	v_mfma_i32_16x16x64_i8 v[98:101], v[178:181], v[194:197], v[98:101]
	v_mfma_i32_16x16x64_i8 v[86:89], v[170:173], v[202:205], v[86:89]
	v_mfma_i32_16x16x64_i8 v[82:85], v[178:181], v[202:205], v[82:85]
	v_mfma_i32_16x16x64_i8 v[70:73], v[170:173], v[210:213], v[70:73]
	v_mfma_i32_16x16x64_i8 v[66:69], v[178:181], v[210:213], v[66:69]
	v_mfma_i32_16x16x64_i8 v[118:121], v[174:177], v[190:193], v[118:121]
	v_mfma_i32_16x16x64_i8 v[114:117], v[182:185], v[190:193], v[114:117]
	v_mfma_i32_16x16x64_i8 v[102:105], v[174:177], v[198:201], v[102:105]
	v_mfma_i32_16x16x64_i8 v[98:101], v[182:185], v[198:201], v[98:101]
	v_mfma_i32_16x16x64_i8 v[86:89], v[174:177], v[206:209], v[86:89]
	v_mfma_i32_16x16x64_i8 v[82:85], v[182:185], v[206:209], v[82:85]
	v_mfma_i32_16x16x64_i8 v[70:73], v[174:177], v[214:217], v[70:73]
	v_mfma_i32_16x16x64_i8 v[66:69], v[182:185], v[214:217], v[66:69]
	s_barrier
	s_setprio 0
	s_add_i32 s36, s61, s51
	v_lshl_add_u64 v[162:163], s[44:45], 0, v[150:151]
	s_mov_b32 m0, s36
	ds_read_b128 v[186:189], v169 offset:16384
	ds_read_b128 v[190:193], v169 offset:17408
	ds_read_b128 v[194:197], v169 offset:18432
	ds_read_b128 v[198:201], v169 offset:19456
	ds_read_b128 v[202:205], v169 offset:20480
	ds_read_b128 v[206:209], v169 offset:21504
	ds_read_b128 v[210:213], v169 offset:22528
	ds_read_b128 v[214:217], v169 offset:23552
	global_load_lds_dwordx4 v[162:163], off
	s_add_i32 m0, s36, 0x2000
	s_add_u32 s36, s44, 0x158000
	v_lshl_add_u64 v[218:219], s[44:45], 0, v[146:147]
	s_addc_u32 s37, s45, 0
	s_add_i32 s78, s62, s51
	global_load_lds_dwordx4 v[218:219], off
	v_lshl_add_u64 v[220:221], s[36:37], 0, v[150:151]
	s_mov_b32 m0, s78
	v_lshl_add_u64 v[222:223], s[46:47], 0, v[148:149]
	global_load_lds_dwordx4 v[220:221], off
	v_lshl_add_u64 v[220:221], s[36:37], 0, v[146:147]
	s_add_i32 m0, s78, 0x2000
	s_nop 0
	global_load_lds_dwordx4 v[220:221], off
	v_lshl_add_u64 v[220:221], s[46:47], 0, v[152:153]
	s_mov_b32 m0, s52
	s_nop 0
	global_load_lds_dwordx4 v[220:221], off
	s_mov_b32 m0, s53
	s_nop 0
	global_load_lds_dwordx4 v[222:223], off
	s_setprio 1
	s_waitcnt vmcnt(8) lgkmcnt(0)
	s_barrier
	v_mfma_i32_16x16x64_i8 v[62:65], v[130:133], v[186:189], v[62:65]
	v_mfma_i32_16x16x64_i8 v[58:61], v[138:141], v[186:189], v[58:61]
	v_mfma_i32_16x16x64_i8 v[46:49], v[130:133], v[194:197], v[46:49]
	v_mfma_i32_16x16x64_i8 v[42:45], v[138:141], v[194:197], v[42:45]
	v_mfma_i32_16x16x64_i8 v[30:33], v[130:133], v[202:205], v[30:33]
	v_mfma_i32_16x16x64_i8 v[26:29], v[138:141], v[202:205], v[26:29]
	v_mfma_i32_16x16x64_i8 v[14:17], v[130:133], v[210:213], v[14:17]
	v_mfma_i32_16x16x64_i8 v[10:13], v[138:141], v[210:213], v[10:13]
	v_mfma_i32_16x16x64_i8 v[62:65], v[134:137], v[190:193], v[62:65]
	v_mfma_i32_16x16x64_i8 v[58:61], v[142:145], v[190:193], v[58:61]
	v_mfma_i32_16x16x64_i8 v[46:49], v[134:137], v[198:201], v[46:49]
	v_mfma_i32_16x16x64_i8 v[42:45], v[142:145], v[198:201], v[42:45]
	v_mfma_i32_16x16x64_i8 v[30:33], v[134:137], v[206:209], v[30:33]
	v_mfma_i32_16x16x64_i8 v[26:29], v[142:145], v[206:209], v[26:29]
	v_mfma_i32_16x16x64_i8 v[14:17], v[134:137], v[214:217], v[14:17]
	v_mfma_i32_16x16x64_i8 v[10:13], v[142:145], v[214:217], v[10:13]
	v_mfma_i32_16x16x64_i8 v[54:57], v[170:173], v[186:189], v[54:57]
	v_mfma_i32_16x16x64_i8 v[50:53], v[178:181], v[186:189], v[50:53]
	v_mfma_i32_16x16x64_i8 v[38:41], v[170:173], v[194:197], v[38:41]
	v_mfma_i32_16x16x64_i8 v[34:37], v[178:181], v[194:197], v[34:37]
	v_mfma_i32_16x16x64_i8 v[22:25], v[170:173], v[202:205], v[22:25]
	v_mfma_i32_16x16x64_i8 v[18:21], v[178:181], v[202:205], v[18:21]
	v_mfma_i32_16x16x64_i8 v[6:9], v[170:173], v[210:213], v[6:9]
	v_mfma_i32_16x16x64_i8 v[2:5], v[178:181], v[210:213], v[2:5]
	v_mfma_i32_16x16x64_i8 v[54:57], v[174:177], v[190:193], v[54:57]
	v_mfma_i32_16x16x64_i8 v[50:53], v[182:185], v[190:193], v[50:53]
	v_mfma_i32_16x16x64_i8 v[38:41], v[174:177], v[198:201], v[38:41]
	v_mfma_i32_16x16x64_i8 v[34:37], v[182:185], v[198:201], v[34:37]
	v_mfma_i32_16x16x64_i8 v[22:25], v[174:177], v[206:209], v[22:25]
	v_mfma_i32_16x16x64_i8 v[18:21], v[182:185], v[206:209], v[18:21]
	v_mfma_i32_16x16x64_i8 v[6:9], v[174:177], v[214:217], v[6:9]
	v_mfma_i32_16x16x64_i8 v[2:5], v[182:185], v[214:217], v[2:5]
	s_barrier
	s_setprio 0
	s_add_i32 s78, 0, 0x18000
	s_add_i32 s79, 0, 0x1c000
	v_add_u32_e32 v142, s78, v166
	v_add_u32_e32 v182, s79, v166
	ds_read_b128 v[130:133], v142
	ds_read_b128 v[134:137], v142 offset:1024
	ds_read_b128 v[138:141], v142 offset:2048
	ds_read_b128 v[142:145], v142 offset:3072
	ds_read_b128 v[170:173], v182
	ds_read_b128 v[174:177], v182 offset:1024
	ds_read_b128 v[178:181], v182 offset:2048
	ds_read_b128 v[182:185], v182 offset:3072
	s_add_u32 s36, s46, 0x158000
	s_addc_u32 s37, s47, 0
	s_mov_b32 m0, s54
	v_lshl_add_u64 v[224:225], s[36:37], 0, v[152:153]
	ds_read_b128 v[186:189], v169 offset:32768
	ds_read_b128 v[190:193], v169 offset:33792
	ds_read_b128 v[194:197], v169 offset:34816
	ds_read_b128 v[198:201], v169 offset:35840
	ds_read_b128 v[202:205], v169 offset:36864
	ds_read_b128 v[206:209], v169 offset:37888
	ds_read_b128 v[210:213], v169 offset:38912
	ds_read_b128 v[214:217], v169 offset:39936
	global_load_lds_dwordx4 v[224:225], off
	v_lshl_add_u64 v[224:225], s[36:37], 0, v[148:149]
	s_mov_b32 m0, s55
	s_nop 0
	global_load_lds_dwordx4 v[224:225], off
	s_setprio 1
	s_waitcnt vmcnt(8) lgkmcnt(0)
	s_barrier
	v_mfma_i32_16x16x64_i8 v[126:129], v[130:133], v[186:189], v[126:129]
	v_mfma_i32_16x16x64_i8 v[122:125], v[138:141], v[186:189], v[122:125]
	v_mfma_i32_16x16x64_i8 v[110:113], v[130:133], v[194:197], v[110:113]
	v_mfma_i32_16x16x64_i8 v[106:109], v[138:141], v[194:197], v[106:109]
	v_mfma_i32_16x16x64_i8 v[94:97], v[130:133], v[202:205], v[94:97]
	v_mfma_i32_16x16x64_i8 v[90:93], v[138:141], v[202:205], v[90:93]
	v_mfma_i32_16x16x64_i8 v[78:81], v[130:133], v[210:213], v[78:81]
	v_mfma_i32_16x16x64_i8 v[74:77], v[138:141], v[210:213], v[74:77]
	v_mfma_i32_16x16x64_i8 v[126:129], v[134:137], v[190:193], v[126:129]
	v_mfma_i32_16x16x64_i8 v[122:125], v[142:145], v[190:193], v[122:125]
	v_mfma_i32_16x16x64_i8 v[110:113], v[134:137], v[198:201], v[110:113]
	v_mfma_i32_16x16x64_i8 v[106:109], v[142:145], v[198:201], v[106:109]
	v_mfma_i32_16x16x64_i8 v[94:97], v[134:137], v[206:209], v[94:97]
	v_mfma_i32_16x16x64_i8 v[90:93], v[142:145], v[206:209], v[90:93]
	v_mfma_i32_16x16x64_i8 v[78:81], v[134:137], v[214:217], v[78:81]
	v_mfma_i32_16x16x64_i8 v[74:77], v[142:145], v[214:217], v[74:77]
	v_mfma_i32_16x16x64_i8 v[118:121], v[170:173], v[186:189], v[118:121]
	v_mfma_i32_16x16x64_i8 v[114:117], v[178:181], v[186:189], v[114:117]
	v_mfma_i32_16x16x64_i8 v[102:105], v[170:173], v[194:197], v[102:105]
	v_mfma_i32_16x16x64_i8 v[98:101], v[178:181], v[194:197], v[98:101]
	v_mfma_i32_16x16x64_i8 v[86:89], v[170:173], v[202:205], v[86:89]
	v_mfma_i32_16x16x64_i8 v[82:85], v[178:181], v[202:205], v[82:85]
	v_mfma_i32_16x16x64_i8 v[70:73], v[170:173], v[210:213], v[70:73]
	v_mfma_i32_16x16x64_i8 v[66:69], v[178:181], v[210:213], v[66:69]
	v_mfma_i32_16x16x64_i8 v[118:121], v[174:177], v[190:193], v[118:121]
	v_mfma_i32_16x16x64_i8 v[114:117], v[182:185], v[190:193], v[114:117]
	v_mfma_i32_16x16x64_i8 v[102:105], v[174:177], v[198:201], v[102:105]
	v_mfma_i32_16x16x64_i8 v[98:101], v[182:185], v[198:201], v[98:101]
	v_mfma_i32_16x16x64_i8 v[86:89], v[174:177], v[206:209], v[86:89]
	v_mfma_i32_16x16x64_i8 v[82:85], v[182:185], v[206:209], v[82:85]
	v_mfma_i32_16x16x64_i8 v[70:73], v[174:177], v[214:217], v[70:73]
	v_mfma_i32_16x16x64_i8 v[66:69], v[182:185], v[214:217], v[66:69]
	s_barrier
	s_setprio 0
	s_add_i32 s36, s78, s51
	v_lshl_add_u64 v[162:163], v[162:163], 0, s[14:15]
	s_mov_b32 m0, s36
	ds_read_b128 v[186:189], v169 offset:49152
	ds_read_b128 v[190:193], v169 offset:50176
	ds_read_b128 v[194:197], v169 offset:51200
	ds_read_b128 v[198:201], v169 offset:52224
	ds_read_b128 v[202:205], v169 offset:53248
	ds_read_b128 v[206:209], v169 offset:54272
	ds_read_b128 v[210:213], v169 offset:55296
	ds_read_b128 v[214:217], v169 offset:56320
	global_load_lds_dwordx4 v[162:163], off
	s_add_i32 m0, s36, 0x2000
	s_add_u32 s36, s44, 0x158080
	v_lshl_add_u64 v[162:163], v[218:219], 0, s[14:15]
	s_addc_u32 s37, s45, 0
	s_add_i32 s44, s79, s51
	global_load_lds_dwordx4 v[162:163], off
	v_lshl_add_u64 v[162:163], s[36:37], 0, v[150:151]
	s_mov_b32 m0, s44
	s_nop 0
	global_load_lds_dwordx4 v[162:163], off
	v_lshl_add_u64 v[162:163], s[36:37], 0, v[146:147]
	s_add_i32 m0, s44, 0x2000
	s_nop 0
	global_load_lds_dwordx4 v[162:163], off
	v_lshl_add_u64 v[162:163], v[220:221], 0, s[14:15]
	s_mov_b32 m0, s59
	s_nop 0
	global_load_lds_dwordx4 v[162:163], off
	v_lshl_add_u64 v[162:163], v[222:223], 0, s[14:15]
	s_mov_b32 m0, s60
	s_nop 0
	global_load_lds_dwordx4 v[162:163], off
	s_setprio 1
	s_waitcnt vmcnt(8) lgkmcnt(0)
	s_barrier
	v_mfma_i32_16x16x64_i8 v[62:65], v[130:133], v[186:189], v[62:65]
	v_mfma_i32_16x16x64_i8 v[58:61], v[138:141], v[186:189], v[58:61]
	v_mfma_i32_16x16x64_i8 v[46:49], v[130:133], v[194:197], v[46:49]
	v_mfma_i32_16x16x64_i8 v[42:45], v[138:141], v[194:197], v[42:45]
	v_mfma_i32_16x16x64_i8 v[30:33], v[130:133], v[202:205], v[30:33]
	v_mfma_i32_16x16x64_i8 v[26:29], v[138:141], v[202:205], v[26:29]
	v_mfma_i32_16x16x64_i8 v[14:17], v[130:133], v[210:213], v[14:17]
	v_mfma_i32_16x16x64_i8 v[10:13], v[138:141], v[210:213], v[10:13]
	v_mfma_i32_16x16x64_i8 v[62:65], v[134:137], v[190:193], v[62:65]
	v_mfma_i32_16x16x64_i8 v[58:61], v[142:145], v[190:193], v[58:61]
	v_mfma_i32_16x16x64_i8 v[46:49], v[134:137], v[198:201], v[46:49]
	v_mfma_i32_16x16x64_i8 v[42:45], v[142:145], v[198:201], v[42:45]
	v_mfma_i32_16x16x64_i8 v[30:33], v[134:137], v[206:209], v[30:33]
	v_mfma_i32_16x16x64_i8 v[26:29], v[142:145], v[206:209], v[26:29]
	v_mfma_i32_16x16x64_i8 v[14:17], v[134:137], v[214:217], v[14:17]
	v_mfma_i32_16x16x64_i8 v[10:13], v[142:145], v[214:217], v[10:13]
	v_mfma_i32_16x16x64_i8 v[54:57], v[170:173], v[186:189], v[54:57]
	v_mfma_i32_16x16x64_i8 v[50:53], v[178:181], v[186:189], v[50:53]
	v_mfma_i32_16x16x64_i8 v[38:41], v[170:173], v[194:197], v[38:41]
	v_mfma_i32_16x16x64_i8 v[34:37], v[178:181], v[194:197], v[34:37]
	v_mfma_i32_16x16x64_i8 v[22:25], v[170:173], v[202:205], v[22:25]
	v_mfma_i32_16x16x64_i8 v[18:21], v[178:181], v[202:205], v[18:21]
	v_mfma_i32_16x16x64_i8 v[6:9], v[170:173], v[210:213], v[6:9]
	v_mfma_i32_16x16x64_i8 v[2:5], v[178:181], v[210:213], v[2:5]
	v_mfma_i32_16x16x64_i8 v[54:57], v[174:177], v[190:193], v[54:57]
	v_mfma_i32_16x16x64_i8 v[50:53], v[182:185], v[190:193], v[50:53]
	v_mfma_i32_16x16x64_i8 v[38:41], v[174:177], v[198:201], v[38:41]
	v_mfma_i32_16x16x64_i8 v[34:37], v[182:185], v[198:201], v[34:37]
	v_mfma_i32_16x16x64_i8 v[22:25], v[174:177], v[206:209], v[22:25]
	v_mfma_i32_16x16x64_i8 v[18:21], v[182:185], v[206:209], v[18:21]
	v_mfma_i32_16x16x64_i8 v[6:9], v[174:177], v[214:217], v[6:9]
	v_mfma_i32_16x16x64_i8 v[2:5], v[182:185], v[214:217], v[2:5]
	s_barrier
	s_setprio 0
	s_add_i32 s77, s77, 2
	s_add_u32 s75, s75, 0x100
	s_addc_u32 s76, s76, 0
	s_cmpk_gt_u32 s77, 0x53
	s_mov_b64 s[36:37], s[38:39]
	s_cbranch_scc0 .LBB0_1951
	s_and_b64 vcc, exec, s[16:17]
	s_cbranch_vccz .LBB0_1954
	s_barrier
